# adds hand-written software-pipelined hyena pre-pass tile loop
# speedup vs baseline: 1.0433x; 1.0062x over previous
; DI int tidx() { return tid512() & 255; }
; DI int vbid() { return 2 * (int)blockIdx.x + vhalf(); }
; DI float log_sigmoid(float x) { return fminf(x, 0.f) - log1pf(expf(-fabsf(x))); }
; DI void hyena_pre_tile(const Params& p, int item, char* smem) {
;   const int tid = tidx();
;   const int ct = item & 7, st = (item >> 3) & 63, b = item >> 9;
;   const bf16_t* HY = (const bf16_t*)(p.ws + OFF_HY) + (size_t)b * 4096 * 1536;
;   bf16_t* sT = (bf16_t*)smem;
;   __syncthreads();
; #pragma unroll
;   for (int i = 0; i < 2; ++i) {
;     int row = (tid >> 3) + 32 * i, ck = tid & 7, s = st * 64 + row, c = ct * 64 + ck * 8;
;     float x1[8], vv[8];
; #pragma unroll
;     for (int j = 0; j < 8; ++j) { x1[j] = 0.f; vv[j] = 0.f; }
; #pragma unroll
;     for (int d = -1; d <= 1; ++d) {
;       int ss = s + d;
;       if (ss >= 0 && ss < 4096) {
;         u32x4 a = ldg16(HY + (size_t)ss * 1536 + 512 + c), bb = ldg16(HY + (size_t)ss * 1536 + 1024 + c);
;         float wa[8], wb[8]; ld8f(p.c_short + (d + 1) * 1536 + 512 + c, wa); ld8f(p.c_short + (d + 1) * 1536 + 1024 + c, wb);
; DI void phase10(const Params& p, char* smem) {
;   for (int it = vbid(); it < P10_KV + P10_HY; it += vgrid()) {
;     if (it < P10_KV) {
;       int dir = it & 1, unit = it >> 1;
;       int n = unit & 31, bh = unit >> 5, hh = bh & 3;
;       float lg = log_sigmoid(dir ? p.c_decay_b[hh] : p.c_decay_f[hh]) * LOG2E;
;       LoadStrided al{(const bf16_t*)(p.ws + OFF_RVT) + (size_t)bh * 128 * 4096 + n * 128};
;       LoadKtScaled bl{(const bf16_t*)(p.ws + OFF_RKT) + (size_t)bh * 128 * 4096 + n * 128, lg, dir};
;       EpKV ep{(bf16_t*)(p.ws + (dir ? OFF_KVB : OFF_KVF)) + (size_t)unit * 16384};
;       gemm_tile(al, bl, ep, 128, smem);
;     } else {
;       hyena_pre_tile(p, it - P10_KV, smem);
;     }
.LBB0_848:
	s_cmpk_gt_i32 s33, 0x7ff
	s_mov_b64 s[30:31], -1
	s_cbranch_scc0 .LBB0_854
	s_cmp_lg_u32 s68, 0x200
	s_cbranch_scc1 .Lpre_fallback
	s_cmp_ge_u32 s33, 0xa00
	s_cbranch_scc1 .Lpre_fallback
	s_sub_u32 s1, s33, 0x800
	s_and_b32 s2, s1, 7
	s_lshr_b32 s3, s1, 3
	s_and_b32 s3, s3, 63
	v_readlane_b32 s20, v246, 31
	v_readlane_b32 s21, v246, 32
	v_readlane_b32 s22, v247, 40
	v_readlane_b32 s23, v247, 41
	v_and_b32_e32 v200, 0xff, v196
	v_lshrrev_b32_e32 v201, 3, v200
	v_and_b32_e32 v202, 7, v200
	s_lshl_b32 s6, s3, 6
	v_add_u32_e32 v206, s6, v201
	s_movk_i32 s7, 0xc00
	v_mul_lo_u32 v207, v206, s7
	s_lshl_b32 s10, s2, 7
	v_lshl_add_u32 v208, v202, 4, s10
	v_add_u32_e32 v207, v207, v208
	v_add_u32_e32 v207, 0x800, v207
	s_add_u32 s24, s20, 0x15af0000
	s_addc_u32 s25, s21, 0
	v_mov_b32_e32 v192, v207
	v_mov_b32_e32 v193, 0
	v_lshl_add_u64 v[192:193], s[24:25], 0, v[192:193]
	s_mov_b32 s26, 0x18000
	s_mov_b32 s27, 0
	v_lshl_add_u64 v[194:195], v[192:193], 0, s[26:27]
	s_lshl_b32 s4, s2, 6
	v_add_u32_e32 v203, s4, v201
	v_lshlrev_b32_e32 v203, 16, v203
	s_lshl_b32 s5, s3, 7
	v_lshl_add_u32 v204, v202, 4, s5
	v_add_u32_e32 v203, v203, v204
	v_mov_b32_e32 v198, v203
	v_mov_b32_e32 v199, 0
	v_lshl_add_u64 v[198:199], s[84:85], 0, v[198:199]
	s_mov_b32 s26, 0x200000
	v_lshl_add_u64 v[210:211], v[198:199], 0, s[26:27]
	v_lshlrev_b32_e32 v212, 1, v208
	v_mov_b32_e32 v213, 0
	v_lshl_add_u64 v[212:213], s[22:23], 0, v[212:213]
	s_mov_b32 s26, 0x1800
	v_lshl_add_u64 v[214:215], v[212:213], 0, s[26:27]
	v_lshl_add_u64 v[216:217], v[214:215], 0, s[26:27]
	global_load_dwordx4 v[96:99], v[212:213], off offset:2048
	global_load_dwordx4 v[100:103], v[212:213], off offset:2064
	global_load_dwordx4 v[112:115], v[214:215], off offset:2048
	global_load_dwordx4 v[116:119], v[214:215], off offset:2064
	global_load_dwordx4 v[128:131], v[216:217], off offset:2048
	global_load_dwordx4 v[132:135], v[216:217], off offset:2064
	s_mov_b32 s26, 0x1000
	v_lshl_add_u64 v[212:213], v[212:213], 0, s[26:27]
	v_lshl_add_u64 v[214:215], v[214:215], 0, s[26:27]
	v_lshl_add_u64 v[216:217], v[216:217], 0, s[26:27]
	global_load_dwordx4 v[104:107], v[212:213], off
	global_load_dwordx4 v[108:111], v[212:213], off offset:16
	global_load_dwordx4 v[120:123], v[214:215], off
	global_load_dwordx4 v[124:127], v[214:215], off offset:16
	global_load_dwordx4 v[136:139], v[216:217], off
	global_load_dwordx4 v[140:143], v[216:217], off offset:16
	v_cmp_ne_u32_e64 s[44:45], 0, v206
	v_add_u32_e32 v218, 32, v206
	s_movk_i32 s7, 0xfff
	v_cmp_ne_u32_e64 s[46:47], s7, v218
	v_mul_u32_u24_e32 v219, 0x480, v202
	v_lshl_add_u32 v219, v201, 1, v219
	v_add_u32_e32 v219, s41, v219
	v_mul_u32_u24_e32 v220, 0x90, v201
	v_lshl_add_u32 v220, v202, 4, v220
	v_add_u32_e32 v220, s41, v220
	s_mov_b32 s48, 0xc00000
	s_mov_b32 s49, 0
	s_mov_b32 s50, 0x2000
	s_mov_b32 s51, 0
	global_load_dwordx4 v[0:3], v[192:193], off offset:-4096
	global_load_dwordx4 v[4:7], v[192:193], off offset:-3072
	global_load_dwordx4 v[8:11], v[192:193], off offset:-1024
	global_load_dwordx4 v[12:15], v[192:193], off offset:0
	global_load_dwordx4 v[16:19], v[192:193], off offset:2048
	global_load_dwordx4 v[20:23], v[192:193], off offset:3072
	global_load_dwordx4 v[24:27], v[194:195], off offset:-4096
	global_load_dwordx4 v[28:31], v[194:195], off offset:-3072
	global_load_dwordx4 v[32:35], v[194:195], off offset:-1024
	global_load_dwordx4 v[36:39], v[194:195], off offset:0
	global_load_dwordx4 v[40:43], v[194:195], off offset:2048
	global_load_dwordx4 v[44:47], v[194:195], off offset:3072
	v_lshl_add_u64 v[192:193], v[192:193], 0, s[48:49]
	v_lshl_add_u64 v[194:195], v[194:195], 0, s[48:49]
	s_barrier
	global_load_dwordx4 v[48:51], v[192:193], off offset:-4096
	global_load_dwordx4 v[52:55], v[192:193], off offset:-3072
	global_load_dwordx4 v[56:59], v[192:193], off offset:-1024
	global_load_dwordx4 v[60:63], v[192:193], off offset:0
	global_load_dwordx4 v[64:67], v[192:193], off offset:2048
	global_load_dwordx4 v[68:71], v[192:193], off offset:3072
	global_load_dwordx4 v[72:75], v[194:195], off offset:-4096
	global_load_dwordx4 v[76:79], v[194:195], off offset:-3072
	global_load_dwordx4 v[80:83], v[194:195], off offset:-1024
	global_load_dwordx4 v[84:87], v[194:195], off offset:0
	global_load_dwordx4 v[88:91], v[194:195], off offset:2048
	global_load_dwordx4 v[92:95], v[194:195], off offset:3072
	v_lshl_add_u64 v[192:193], v[192:193], 0, s[48:49]
	v_lshl_add_u64 v[194:195], v[194:195], 0, s[48:49]
	s_waitcnt vmcnt(12)
; DI float bflo(unsigned u) { return __uint_as_float(u << 16); }
; DI float bfhi(unsigned u) { return __uint_as_float(u & 0xffff0000u); }
; DI bf16_t f2bf(float x) { return (bf16_t)(pack2(x, 0.f) & 0xffffu); }
; DI void hyena_pre_tile(const Params& p, int item, char* smem) {
;     ...
;     float x1[8], vv[8];
; #pragma unroll
;     for (int j = 0; j < 8; ++j) { x1[j] = 0.f; vv[j] = 0.f; }
; #pragma unroll
;     for (int d = -1; d <= 1; ++d) {
;       int ss = s + d;
;       if (ss >= 0 && ss < 4096) {
;         u32x4 a = ldg16(HY + (size_t)ss * 1536 + 512 + c), bb = ldg16(HY + (size_t)ss * 1536 + 1024 + c);
;         float wa[8], wb[8]; ld8f(p.c_short + (d + 1) * 1536 + 512 + c, wa); ld8f(p.c_short + (d + 1) * 1536 + 1024 + c, wb);
; #pragma unroll
;         for (int q = 0; q < 4; ++q) {
;           x1[2 * q] += wa[2 * q] * bflo(a[q]); x1[2 * q + 1] += wa[2 * q + 1] * bfhi(a[q]);
;           vv[2 * q] += wb[2 * q] * bflo(bb[q]); vv[2 * q + 1] += wb[2 * q + 1] * bfhi(bb[q]);
;         }
;       }
;     }
; #pragma unroll
;     for (int j = 0; j < 8; ++j) sT[(ck * 8 + j) * 72 + row] = f2bf(x1[j] * vv[j]);
	v_cndmask_b32_e64 v0, 0, v0, s[44:45]
	v_cndmask_b32_e64 v1, 0, v1, s[44:45]
	v_cndmask_b32_e64 v2, 0, v2, s[44:45]
	v_cndmask_b32_e64 v3, 0, v3, s[44:45]
	v_cndmask_b32_e64 v4, 0, v4, s[44:45]
	v_cndmask_b32_e64 v5, 0, v5, s[44:45]
	v_cndmask_b32_e64 v6, 0, v6, s[44:45]
	v_cndmask_b32_e64 v7, 0, v7, s[44:45]
	v_lshlrev_b32_e32 v228, 16, v0
	v_and_b32_e32 v229, 0xffff0000, v0
	v_pk_fma_f32 v[224:225], v[96:97], v[228:229], 0 op_sel_hi:[1,1,0]
	v_lshlrev_b32_e32 v228, 16, v8
	v_and_b32_e32 v229, 0xffff0000, v8
	v_pk_fma_f32 v[224:225], v[112:113], v[228:229], v[224:225]
	v_lshlrev_b32_e32 v228, 16, v16
	v_and_b32_e32 v229, 0xffff0000, v16
	v_pk_fma_f32 v[224:225], v[128:129], v[228:229], v[224:225]
	v_lshlrev_b32_e32 v228, 16, v4
	v_and_b32_e32 v229, 0xffff0000, v4
	v_pk_fma_f32 v[226:227], v[104:105], v[228:229], 0 op_sel_hi:[1,1,0]
	v_lshlrev_b32_e32 v228, 16, v12
	v_and_b32_e32 v229, 0xffff0000, v12
	v_pk_fma_f32 v[226:227], v[120:121], v[228:229], v[226:227]
	v_lshlrev_b32_e32 v228, 16, v20
	v_and_b32_e32 v229, 0xffff0000, v20
	v_pk_fma_f32 v[226:227], v[136:137], v[228:229], v[226:227]
	v_pk_mul_f32 v[224:225], v[224:225], v[226:227]
	v_cvt_pk_bf16_f32 v230, v224, v225
	ds_write_b16 v219, v230
	ds_write_b16_d16_hi v219, v230 offset:144
	v_lshlrev_b32_e32 v228, 16, v1
	v_and_b32_e32 v229, 0xffff0000, v1
	v_pk_fma_f32 v[224:225], v[98:99], v[228:229], 0 op_sel_hi:[1,1,0]
	v_lshlrev_b32_e32 v228, 16, v9
	v_and_b32_e32 v229, 0xffff0000, v9
	v_pk_fma_f32 v[224:225], v[114:115], v[228:229], v[224:225]
	v_lshlrev_b32_e32 v228, 16, v17
	v_and_b32_e32 v229, 0xffff0000, v17
	v_pk_fma_f32 v[224:225], v[130:131], v[228:229], v[224:225]
	v_lshlrev_b32_e32 v228, 16, v5
	v_and_b32_e32 v229, 0xffff0000, v5
	v_pk_fma_f32 v[226:227], v[106:107], v[228:229], 0 op_sel_hi:[1,1,0]
	v_lshlrev_b32_e32 v228, 16, v13
	v_and_b32_e32 v229, 0xffff0000, v13
	v_pk_fma_f32 v[226:227], v[122:123], v[228:229], v[226:227]
	v_lshlrev_b32_e32 v228, 16, v21
	v_and_b32_e32 v229, 0xffff0000, v21
	v_pk_fma_f32 v[226:227], v[138:139], v[228:229], v[226:227]
	v_pk_mul_f32 v[224:225], v[224:225], v[226:227]
	v_cvt_pk_bf16_f32 v230, v224, v225
	ds_write_b16 v219, v230 offset:288
	ds_write_b16_d16_hi v219, v230 offset:432
	v_lshlrev_b32_e32 v228, 16, v2
	v_and_b32_e32 v229, 0xffff0000, v2
	v_pk_fma_f32 v[224:225], v[100:101], v[228:229], 0 op_sel_hi:[1,1,0]
	v_lshlrev_b32_e32 v228, 16, v10
	v_and_b32_e32 v229, 0xffff0000, v10
	v_pk_fma_f32 v[224:225], v[116:117], v[228:229], v[224:225]
	v_lshlrev_b32_e32 v228, 16, v18
	v_and_b32_e32 v229, 0xffff0000, v18
	v_pk_fma_f32 v[224:225], v[132:133], v[228:229], v[224:225]
	v_lshlrev_b32_e32 v228, 16, v6
	v_and_b32_e32 v229, 0xffff0000, v6
	v_pk_fma_f32 v[226:227], v[108:109], v[228:229], 0 op_sel_hi:[1,1,0]
	v_lshlrev_b32_e32 v228, 16, v14
	v_and_b32_e32 v229, 0xffff0000, v14
	v_pk_fma_f32 v[226:227], v[124:125], v[228:229], v[226:227]
	v_lshlrev_b32_e32 v228, 16, v22
	v_and_b32_e32 v229, 0xffff0000, v22
	v_pk_fma_f32 v[226:227], v[140:141], v[228:229], v[226:227]
	v_pk_mul_f32 v[224:225], v[224:225], v[226:227]
	v_cvt_pk_bf16_f32 v230, v224, v225
	ds_write_b16 v219, v230 offset:576
	ds_write_b16_d16_hi v219, v230 offset:720
	v_lshlrev_b32_e32 v228, 16, v3
	v_and_b32_e32 v229, 0xffff0000, v3
	v_pk_fma_f32 v[224:225], v[102:103], v[228:229], 0 op_sel_hi:[1,1,0]
	v_lshlrev_b32_e32 v228, 16, v11
	v_and_b32_e32 v229, 0xffff0000, v11
	v_pk_fma_f32 v[224:225], v[118:119], v[228:229], v[224:225]
	v_lshlrev_b32_e32 v228, 16, v19
	v_and_b32_e32 v229, 0xffff0000, v19
	v_pk_fma_f32 v[224:225], v[134:135], v[228:229], v[224:225]
	v_lshlrev_b32_e32 v228, 16, v7
	v_and_b32_e32 v229, 0xffff0000, v7
	v_pk_fma_f32 v[226:227], v[110:111], v[228:229], 0 op_sel_hi:[1,1,0]
	v_lshlrev_b32_e32 v228, 16, v15
	v_and_b32_e32 v229, 0xffff0000, v15
	v_pk_fma_f32 v[226:227], v[126:127], v[228:229], v[226:227]
	v_lshlrev_b32_e32 v228, 16, v23
	v_and_b32_e32 v229, 0xffff0000, v23
	v_pk_fma_f32 v[226:227], v[142:143], v[228:229], v[226:227]
	v_pk_mul_f32 v[224:225], v[224:225], v[226:227]
	v_cvt_pk_bf16_f32 v230, v224, v225
	ds_write_b16 v219, v230 offset:864
	ds_write_b16_d16_hi v219, v230 offset:1008
	v_cndmask_b32_e64 v40, 0, v40, s[46:47]
	v_cndmask_b32_e64 v41, 0, v41, s[46:47]
	v_cndmask_b32_e64 v42, 0, v42, s[46:47]
	v_cndmask_b32_e64 v43, 0, v43, s[46:47]
	v_cndmask_b32_e64 v44, 0, v44, s[46:47]
	v_cndmask_b32_e64 v45, 0, v45, s[46:47]
	v_cndmask_b32_e64 v46, 0, v46, s[46:47]
	v_cndmask_b32_e64 v47, 0, v47, s[46:47]
	v_lshlrev_b32_e32 v228, 16, v24
	v_and_b32_e32 v229, 0xffff0000, v24
	v_pk_fma_f32 v[224:225], v[96:97], v[228:229], 0 op_sel_hi:[1,1,0]
	v_lshlrev_b32_e32 v228, 16, v32
	v_and_b32_e32 v229, 0xffff0000, v32
	v_pk_fma_f32 v[224:225], v[112:113], v[228:229], v[224:225]
	v_lshlrev_b32_e32 v228, 16, v40
	v_and_b32_e32 v229, 0xffff0000, v40
	v_pk_fma_f32 v[224:225], v[128:129], v[228:229], v[224:225]
	v_lshlrev_b32_e32 v228, 16, v28
	v_and_b32_e32 v229, 0xffff0000, v28
	v_pk_fma_f32 v[226:227], v[104:105], v[228:229], 0 op_sel_hi:[1,1,0]
	v_lshlrev_b32_e32 v228, 16, v36
	v_and_b32_e32 v229, 0xffff0000, v36
	v_pk_fma_f32 v[226:227], v[120:121], v[228:229], v[226:227]
	v_lshlrev_b32_e32 v228, 16, v44
	v_and_b32_e32 v229, 0xffff0000, v44
	v_pk_fma_f32 v[226:227], v[136:137], v[228:229], v[226:227]
	v_pk_mul_f32 v[224:225], v[224:225], v[226:227]
	v_cvt_pk_bf16_f32 v230, v224, v225
	ds_write_b16 v219, v230 offset:64
	ds_write_b16_d16_hi v219, v230 offset:208
	v_lshlrev_b32_e32 v228, 16, v25
	v_and_b32_e32 v229, 0xffff0000, v25
	v_pk_fma_f32 v[224:225], v[98:99], v[228:229], 0 op_sel_hi:[1,1,0]
	v_lshlrev_b32_e32 v228, 16, v33
	v_and_b32_e32 v229, 0xffff0000, v33
; DI float bflo(unsigned u) { return __uint_as_float(u << 16); }
; DI float bfhi(unsigned u) { return __uint_as_float(u & 0xffff0000u); }
; DI bf16_t f2bf(float x) { return (bf16_t)(pack2(x, 0.f) & 0xffffu); }
; DI void hyena_pre_tile(const Params& p, int item, char* smem) {
;     ...
; #pragma unroll
;         for (int q = 0; q < 4; ++q) {
;           x1[2 * q] += wa[2 * q] * bflo(a[q]); x1[2 * q + 1] += wa[2 * q + 1] * bfhi(a[q]);
;           vv[2 * q] += wb[2 * q] * bflo(bb[q]); vv[2 * q + 1] += wb[2 * q + 1] * bfhi(bb[q]);
;         }
;       }
;     }
; #pragma unroll
;     for (int j = 0; j < 8; ++j) sT[(ck * 8 + j) * 72 + row] = f2bf(x1[j] * vv[j]);
;   }
;   __syncthreads();
;   bf16_t* uT = (bf16_t*)(p.hbuf + HB_UT);
; #pragma unroll
;   for (int i = 0; i < 2; ++i) {
;     int row = (tid >> 3) + 32 * i, ck = tid & 7;
;     *(u32x4*)(uT + ((size_t)(ct * 64 + row) * 8 + b) * 4096 + st * 64 + ck * 8) = *(const u32x4*)(sT + row * 72 + ck * 8);
;   }
	v_pk_fma_f32 v[224:225], v[114:115], v[228:229], v[224:225]
	v_lshlrev_b32_e32 v228, 16, v41
	v_and_b32_e32 v229, 0xffff0000, v41
	v_pk_fma_f32 v[224:225], v[130:131], v[228:229], v[224:225]
	v_lshlrev_b32_e32 v228, 16, v29
	v_and_b32_e32 v229, 0xffff0000, v29
	v_pk_fma_f32 v[226:227], v[106:107], v[228:229], 0 op_sel_hi:[1,1,0]
	v_lshlrev_b32_e32 v228, 16, v37
	v_and_b32_e32 v229, 0xffff0000, v37
	v_pk_fma_f32 v[226:227], v[122:123], v[228:229], v[226:227]
	v_lshlrev_b32_e32 v228, 16, v45
	v_and_b32_e32 v229, 0xffff0000, v45
	v_pk_fma_f32 v[226:227], v[138:139], v[228:229], v[226:227]
	v_pk_mul_f32 v[224:225], v[224:225], v[226:227]
	v_cvt_pk_bf16_f32 v230, v224, v225
	ds_write_b16 v219, v230 offset:352
	ds_write_b16_d16_hi v219, v230 offset:496
	v_lshlrev_b32_e32 v228, 16, v26
	v_and_b32_e32 v229, 0xffff0000, v26
	v_pk_fma_f32 v[224:225], v[100:101], v[228:229], 0 op_sel_hi:[1,1,0]
	v_lshlrev_b32_e32 v228, 16, v34
	v_and_b32_e32 v229, 0xffff0000, v34
	v_pk_fma_f32 v[224:225], v[116:117], v[228:229], v[224:225]
	v_lshlrev_b32_e32 v228, 16, v42
	v_and_b32_e32 v229, 0xffff0000, v42
	v_pk_fma_f32 v[224:225], v[132:133], v[228:229], v[224:225]
	v_lshlrev_b32_e32 v228, 16, v30
	v_and_b32_e32 v229, 0xffff0000, v30
	v_pk_fma_f32 v[226:227], v[108:109], v[228:229], 0 op_sel_hi:[1,1,0]
	v_lshlrev_b32_e32 v228, 16, v38
	v_and_b32_e32 v229, 0xffff0000, v38
	v_pk_fma_f32 v[226:227], v[124:125], v[228:229], v[226:227]
	v_lshlrev_b32_e32 v228, 16, v46
	v_and_b32_e32 v229, 0xffff0000, v46
	v_pk_fma_f32 v[226:227], v[140:141], v[228:229], v[226:227]
	v_pk_mul_f32 v[224:225], v[224:225], v[226:227]
	v_cvt_pk_bf16_f32 v230, v224, v225
	ds_write_b16 v219, v230 offset:640
	ds_write_b16_d16_hi v219, v230 offset:784
	v_lshlrev_b32_e32 v228, 16, v27
	v_and_b32_e32 v229, 0xffff0000, v27
	v_pk_fma_f32 v[224:225], v[102:103], v[228:229], 0 op_sel_hi:[1,1,0]
	v_lshlrev_b32_e32 v228, 16, v35
	v_and_b32_e32 v229, 0xffff0000, v35
	v_pk_fma_f32 v[224:225], v[118:119], v[228:229], v[224:225]
	v_lshlrev_b32_e32 v228, 16, v43
	v_and_b32_e32 v229, 0xffff0000, v43
	v_pk_fma_f32 v[224:225], v[134:135], v[228:229], v[224:225]
	v_lshlrev_b32_e32 v228, 16, v31
	v_and_b32_e32 v229, 0xffff0000, v31
	v_pk_fma_f32 v[226:227], v[110:111], v[228:229], 0 op_sel_hi:[1,1,0]
	v_lshlrev_b32_e32 v228, 16, v39
	v_and_b32_e32 v229, 0xffff0000, v39
	v_pk_fma_f32 v[226:227], v[126:127], v[228:229], v[226:227]
	v_lshlrev_b32_e32 v228, 16, v47
	v_and_b32_e32 v229, 0xffff0000, v47
	v_pk_fma_f32 v[226:227], v[142:143], v[228:229], v[226:227]
	v_pk_mul_f32 v[224:225], v[224:225], v[226:227]
	v_cvt_pk_bf16_f32 v230, v224, v225
	ds_write_b16 v219, v230 offset:928
	ds_write_b16_d16_hi v219, v230 offset:1072
	s_waitcnt lgkmcnt(0)
	s_barrier
	ds_read_b128 v[232:235], v220
	ds_read_b128 v[236:239], v220 offset:4608
	s_waitcnt lgkmcnt(1)
	global_store_dwordx4 v[198:199], v[232:235], off
	s_waitcnt lgkmcnt(0)
	global_store_dwordx4 v[210:211], v[236:239], off
	v_lshl_add_u64 v[198:199], v[198:199], 0, s[50:51]
	v_lshl_add_u64 v[210:211], v[210:211], 0, s[50:51]
	global_load_dwordx4 v[0:3], v[192:193], off offset:-4096
	global_load_dwordx4 v[4:7], v[192:193], off offset:-3072
	global_load_dwordx4 v[8:11], v[192:193], off offset:-1024
	global_load_dwordx4 v[12:15], v[192:193], off offset:0
	global_load_dwordx4 v[16:19], v[192:193], off offset:2048
	global_load_dwordx4 v[20:23], v[192:193], off offset:3072
	global_load_dwordx4 v[24:27], v[194:195], off offset:-4096
	global_load_dwordx4 v[28:31], v[194:195], off offset:-3072
	global_load_dwordx4 v[32:35], v[194:195], off offset:-1024
	global_load_dwordx4 v[36:39], v[194:195], off offset:0
	global_load_dwordx4 v[40:43], v[194:195], off offset:2048
	global_load_dwordx4 v[44:47], v[194:195], off offset:3072
	v_lshl_add_u64 v[192:193], v[192:193], 0, s[48:49]
	v_lshl_add_u64 v[194:195], v[194:195], 0, s[48:49]
	s_waitcnt vmcnt(14)
	v_cndmask_b32_e64 v48, 0, v48, s[44:45]
	v_cndmask_b32_e64 v49, 0, v49, s[44:45]
	v_cndmask_b32_e64 v50, 0, v50, s[44:45]
	v_cndmask_b32_e64 v51, 0, v51, s[44:45]
	v_cndmask_b32_e64 v52, 0, v52, s[44:45]
	v_cndmask_b32_e64 v53, 0, v53, s[44:45]
	v_cndmask_b32_e64 v54, 0, v54, s[44:45]
	v_cndmask_b32_e64 v55, 0, v55, s[44:45]
	v_lshlrev_b32_e32 v228, 16, v48
	v_and_b32_e32 v229, 0xffff0000, v48
	v_pk_fma_f32 v[224:225], v[96:97], v[228:229], 0 op_sel_hi:[1,1,0]
	v_lshlrev_b32_e32 v228, 16, v56
	v_and_b32_e32 v229, 0xffff0000, v56
	v_pk_fma_f32 v[224:225], v[112:113], v[228:229], v[224:225]
	v_lshlrev_b32_e32 v228, 16, v64
	v_and_b32_e32 v229, 0xffff0000, v64
	v_pk_fma_f32 v[224:225], v[128:129], v[228:229], v[224:225]
	v_lshlrev_b32_e32 v228, 16, v52
	v_and_b32_e32 v229, 0xffff0000, v52
	v_pk_fma_f32 v[226:227], v[104:105], v[228:229], 0 op_sel_hi:[1,1,0]
	v_lshlrev_b32_e32 v228, 16, v60
	v_and_b32_e32 v229, 0xffff0000, v60
	v_pk_fma_f32 v[226:227], v[120:121], v[228:229], v[226:227]
	v_lshlrev_b32_e32 v228, 16, v68
	v_and_b32_e32 v229, 0xffff0000, v68
	v_pk_fma_f32 v[226:227], v[136:137], v[228:229], v[226:227]
	v_pk_mul_f32 v[224:225], v[224:225], v[226:227]
	v_cvt_pk_bf16_f32 v230, v224, v225
	ds_write_b16 v219, v230 offset:9216
	ds_write_b16_d16_hi v219, v230 offset:9360
	v_lshlrev_b32_e32 v228, 16, v49
	v_and_b32_e32 v229, 0xffff0000, v49
	v_pk_fma_f32 v[224:225], v[98:99], v[228:229], 0 op_sel_hi:[1,1,0]
	v_lshlrev_b32_e32 v228, 16, v57
	v_and_b32_e32 v229, 0xffff0000, v57
	v_pk_fma_f32 v[224:225], v[114:115], v[228:229], v[224:225]
	v_lshlrev_b32_e32 v228, 16, v65
	v_and_b32_e32 v229, 0xffff0000, v65
	v_pk_fma_f32 v[224:225], v[130:131], v[228:229], v[224:225]
	v_lshlrev_b32_e32 v228, 16, v53
	v_and_b32_e32 v229, 0xffff0000, v53
; DI float bflo(unsigned u) { return __uint_as_float(u << 16); }
; DI float bfhi(unsigned u) { return __uint_as_float(u & 0xffff0000u); }
; DI bf16_t f2bf(float x) { return (bf16_t)(pack2(x, 0.f) & 0xffffu); }
; DI void hyena_pre_tile(const Params& p, int item, char* smem) {
;     ...
;     float x1[8], vv[8];
; #pragma unroll
;     for (int j = 0; j < 8; ++j) { x1[j] = 0.f; vv[j] = 0.f; }
; #pragma unroll
;     for (int d = -1; d <= 1; ++d) {
;       int ss = s + d;
;       if (ss >= 0 && ss < 4096) {
;         u32x4 a = ldg16(HY + (size_t)ss * 1536 + 512 + c), bb = ldg16(HY + (size_t)ss * 1536 + 1024 + c);
;         float wa[8], wb[8]; ld8f(p.c_short + (d + 1) * 1536 + 512 + c, wa); ld8f(p.c_short + (d + 1) * 1536 + 1024 + c, wb);
; #pragma unroll
;         for (int q = 0; q < 4; ++q) {
;           x1[2 * q] += wa[2 * q] * bflo(a[q]); x1[2 * q + 1] += wa[2 * q + 1] * bfhi(a[q]);
;           vv[2 * q] += wb[2 * q] * bflo(bb[q]); vv[2 * q + 1] += wb[2 * q + 1] * bfhi(bb[q]);
;         }
;       }
;     }
; #pragma unroll
;     for (int j = 0; j < 8; ++j) sT[(ck * 8 + j) * 72 + row] = f2bf(x1[j] * vv[j]);
	v_pk_fma_f32 v[226:227], v[106:107], v[228:229], 0 op_sel_hi:[1,1,0]
	v_lshlrev_b32_e32 v228, 16, v61
	v_and_b32_e32 v229, 0xffff0000, v61
	v_pk_fma_f32 v[226:227], v[122:123], v[228:229], v[226:227]
	v_lshlrev_b32_e32 v228, 16, v69
	v_and_b32_e32 v229, 0xffff0000, v69
	v_pk_fma_f32 v[226:227], v[138:139], v[228:229], v[226:227]
	v_pk_mul_f32 v[224:225], v[224:225], v[226:227]
	v_cvt_pk_bf16_f32 v230, v224, v225
	ds_write_b16 v219, v230 offset:9504
	ds_write_b16_d16_hi v219, v230 offset:9648
	v_lshlrev_b32_e32 v228, 16, v50
	v_and_b32_e32 v229, 0xffff0000, v50
	v_pk_fma_f32 v[224:225], v[100:101], v[228:229], 0 op_sel_hi:[1,1,0]
	v_lshlrev_b32_e32 v228, 16, v58
	v_and_b32_e32 v229, 0xffff0000, v58
	v_pk_fma_f32 v[224:225], v[116:117], v[228:229], v[224:225]
	v_lshlrev_b32_e32 v228, 16, v66
	v_and_b32_e32 v229, 0xffff0000, v66
	v_pk_fma_f32 v[224:225], v[132:133], v[228:229], v[224:225]
	v_lshlrev_b32_e32 v228, 16, v54
	v_and_b32_e32 v229, 0xffff0000, v54
	v_pk_fma_f32 v[226:227], v[108:109], v[228:229], 0 op_sel_hi:[1,1,0]
	v_lshlrev_b32_e32 v228, 16, v62
	v_and_b32_e32 v229, 0xffff0000, v62
	v_pk_fma_f32 v[226:227], v[124:125], v[228:229], v[226:227]
	v_lshlrev_b32_e32 v228, 16, v70
	v_and_b32_e32 v229, 0xffff0000, v70
	v_pk_fma_f32 v[226:227], v[140:141], v[228:229], v[226:227]
	v_pk_mul_f32 v[224:225], v[224:225], v[226:227]
	v_cvt_pk_bf16_f32 v230, v224, v225
	ds_write_b16 v219, v230 offset:9792
	ds_write_b16_d16_hi v219, v230 offset:9936
	v_lshlrev_b32_e32 v228, 16, v51
	v_and_b32_e32 v229, 0xffff0000, v51
	v_pk_fma_f32 v[224:225], v[102:103], v[228:229], 0 op_sel_hi:[1,1,0]
	v_lshlrev_b32_e32 v228, 16, v59
	v_and_b32_e32 v229, 0xffff0000, v59
	v_pk_fma_f32 v[224:225], v[118:119], v[228:229], v[224:225]
	v_lshlrev_b32_e32 v228, 16, v67
	v_and_b32_e32 v229, 0xffff0000, v67
	v_pk_fma_f32 v[224:225], v[134:135], v[228:229], v[224:225]
	v_lshlrev_b32_e32 v228, 16, v55
	v_and_b32_e32 v229, 0xffff0000, v55
	v_pk_fma_f32 v[226:227], v[110:111], v[228:229], 0 op_sel_hi:[1,1,0]
	v_lshlrev_b32_e32 v228, 16, v63
	v_and_b32_e32 v229, 0xffff0000, v63
	v_pk_fma_f32 v[226:227], v[126:127], v[228:229], v[226:227]
	v_lshlrev_b32_e32 v228, 16, v71
	v_and_b32_e32 v229, 0xffff0000, v71
	v_pk_fma_f32 v[226:227], v[142:143], v[228:229], v[226:227]
	v_pk_mul_f32 v[224:225], v[224:225], v[226:227]
	v_cvt_pk_bf16_f32 v230, v224, v225
	ds_write_b16 v219, v230 offset:10080
	ds_write_b16_d16_hi v219, v230 offset:10224
	v_cndmask_b32_e64 v88, 0, v88, s[46:47]
	v_cndmask_b32_e64 v89, 0, v89, s[46:47]
	v_cndmask_b32_e64 v90, 0, v90, s[46:47]
	v_cndmask_b32_e64 v91, 0, v91, s[46:47]
	v_cndmask_b32_e64 v92, 0, v92, s[46:47]
	v_cndmask_b32_e64 v93, 0, v93, s[46:47]
	v_cndmask_b32_e64 v94, 0, v94, s[46:47]
	v_cndmask_b32_e64 v95, 0, v95, s[46:47]
	v_lshlrev_b32_e32 v228, 16, v72
	v_and_b32_e32 v229, 0xffff0000, v72
	v_pk_fma_f32 v[224:225], v[96:97], v[228:229], 0 op_sel_hi:[1,1,0]
	v_lshlrev_b32_e32 v228, 16, v80
	v_and_b32_e32 v229, 0xffff0000, v80
	v_pk_fma_f32 v[224:225], v[112:113], v[228:229], v[224:225]
	v_lshlrev_b32_e32 v228, 16, v88
	v_and_b32_e32 v229, 0xffff0000, v88
	v_pk_fma_f32 v[224:225], v[128:129], v[228:229], v[224:225]
	v_lshlrev_b32_e32 v228, 16, v76
	v_and_b32_e32 v229, 0xffff0000, v76
	v_pk_fma_f32 v[226:227], v[104:105], v[228:229], 0 op_sel_hi:[1,1,0]
	v_lshlrev_b32_e32 v228, 16, v84
	v_and_b32_e32 v229, 0xffff0000, v84
	v_pk_fma_f32 v[226:227], v[120:121], v[228:229], v[226:227]
	v_lshlrev_b32_e32 v228, 16, v92
	v_and_b32_e32 v229, 0xffff0000, v92
	v_pk_fma_f32 v[226:227], v[136:137], v[228:229], v[226:227]
	v_pk_mul_f32 v[224:225], v[224:225], v[226:227]
	v_cvt_pk_bf16_f32 v230, v224, v225
	ds_write_b16 v219, v230 offset:9280
	ds_write_b16_d16_hi v219, v230 offset:9424
	v_lshlrev_b32_e32 v228, 16, v73
	v_and_b32_e32 v229, 0xffff0000, v73
	v_pk_fma_f32 v[224:225], v[98:99], v[228:229], 0 op_sel_hi:[1,1,0]
	v_lshlrev_b32_e32 v228, 16, v81
	v_and_b32_e32 v229, 0xffff0000, v81
	v_pk_fma_f32 v[224:225], v[114:115], v[228:229], v[224:225]
	v_lshlrev_b32_e32 v228, 16, v89
	v_and_b32_e32 v229, 0xffff0000, v89
	v_pk_fma_f32 v[224:225], v[130:131], v[228:229], v[224:225]
	v_lshlrev_b32_e32 v228, 16, v77
	v_and_b32_e32 v229, 0xffff0000, v77
	v_pk_fma_f32 v[226:227], v[106:107], v[228:229], 0 op_sel_hi:[1,1,0]
	v_lshlrev_b32_e32 v228, 16, v85
	v_and_b32_e32 v229, 0xffff0000, v85
	v_pk_fma_f32 v[226:227], v[122:123], v[228:229], v[226:227]
	v_lshlrev_b32_e32 v228, 16, v93
	v_and_b32_e32 v229, 0xffff0000, v93
	v_pk_fma_f32 v[226:227], v[138:139], v[228:229], v[226:227]
	v_pk_mul_f32 v[224:225], v[224:225], v[226:227]
	v_cvt_pk_bf16_f32 v230, v224, v225
	ds_write_b16 v219, v230 offset:9568
	ds_write_b16_d16_hi v219, v230 offset:9712
	v_lshlrev_b32_e32 v228, 16, v74
	v_and_b32_e32 v229, 0xffff0000, v74
	v_pk_fma_f32 v[224:225], v[100:101], v[228:229], 0 op_sel_hi:[1,1,0]
	v_lshlrev_b32_e32 v228, 16, v82
	v_and_b32_e32 v229, 0xffff0000, v82
	v_pk_fma_f32 v[224:225], v[116:117], v[228:229], v[224:225]
	v_lshlrev_b32_e32 v228, 16, v90
	v_and_b32_e32 v229, 0xffff0000, v90
	v_pk_fma_f32 v[224:225], v[132:133], v[228:229], v[224:225]
	v_lshlrev_b32_e32 v228, 16, v78
	v_and_b32_e32 v229, 0xffff0000, v78
	v_pk_fma_f32 v[226:227], v[108:109], v[228:229], 0 op_sel_hi:[1,1,0]
	v_lshlrev_b32_e32 v228, 16, v86
	v_and_b32_e32 v229, 0xffff0000, v86
	v_pk_fma_f32 v[226:227], v[124:125], v[228:229], v[226:227]
	v_lshlrev_b32_e32 v228, 16, v94
	v_and_b32_e32 v229, 0xffff0000, v94
	v_pk_fma_f32 v[226:227], v[140:141], v[228:229], v[226:227]
	v_pk_mul_f32 v[224:225], v[224:225], v[226:227]
	v_cvt_pk_bf16_f32 v230, v224, v225
	ds_write_b16 v219, v230 offset:9856
	ds_write_b16_d16_hi v219, v230 offset:10000
	v_lshlrev_b32_e32 v228, 16, v75
	v_and_b32_e32 v229, 0xffff0000, v75
	v_pk_fma_f32 v[224:225], v[102:103], v[228:229], 0 op_sel_hi:[1,1,0]
	v_lshlrev_b32_e32 v228, 16, v83
	v_and_b32_e32 v229, 0xffff0000, v83
	v_pk_fma_f32 v[224:225], v[118:119], v[228:229], v[224:225]
	v_lshlrev_b32_e32 v228, 16, v91
	v_and_b32_e32 v229, 0xffff0000, v91
	v_pk_fma_f32 v[224:225], v[134:135], v[228:229], v[224:225]
	v_lshlrev_b32_e32 v228, 16, v79
	v_and_b32_e32 v229, 0xffff0000, v79
	v_pk_fma_f32 v[226:227], v[110:111], v[228:229], 0 op_sel_hi:[1,1,0]
	v_lshlrev_b32_e32 v228, 16, v87
	v_and_b32_e32 v229, 0xffff0000, v87
	v_pk_fma_f32 v[226:227], v[126:127], v[228:229], v[226:227]
	v_lshlrev_b32_e32 v228, 16, v95
	v_and_b32_e32 v229, 0xffff0000, v95
	v_pk_fma_f32 v[226:227], v[142:143], v[228:229], v[226:227]
	v_pk_mul_f32 v[224:225], v[224:225], v[226:227]
	v_cvt_pk_bf16_f32 v230, v224, v225
	ds_write_b16 v219, v230 offset:10144
	ds_write_b16_d16_hi v219, v230 offset:10288
	s_waitcnt lgkmcnt(0)
	s_barrier
; DI float bflo(unsigned u) { return __uint_as_float(u << 16); }
; DI float bfhi(unsigned u) { return __uint_as_float(u & 0xffff0000u); }
; DI bf16_t f2bf(float x) { return (bf16_t)(pack2(x, 0.f) & 0xffffu); }
; DI void hyena_pre_tile(const Params& p, int item, char* smem) {
;     ...
;     float x1[8], vv[8];
; #pragma unroll
;     for (int j = 0; j < 8; ++j) { x1[j] = 0.f; vv[j] = 0.f; }
; #pragma unroll
;     for (int d = -1; d <= 1; ++d) {
;       int ss = s + d;
;       if (ss >= 0 && ss < 4096) {
;         u32x4 a = ldg16(HY + (size_t)ss * 1536 + 512 + c), bb = ldg16(HY + (size_t)ss * 1536 + 1024 + c);
;         float wa[8], wb[8]; ld8f(p.c_short + (d + 1) * 1536 + 512 + c, wa); ld8f(p.c_short + (d + 1) * 1536 + 1024 + c, wb);
; #pragma unroll
;         for (int q = 0; q < 4; ++q) {
;           x1[2 * q] += wa[2 * q] * bflo(a[q]); x1[2 * q + 1] += wa[2 * q + 1] * bfhi(a[q]);
;           vv[2 * q] += wb[2 * q] * bflo(bb[q]); vv[2 * q + 1] += wb[2 * q + 1] * bfhi(bb[q]);
;         }
;       }
;     }
; #pragma unroll
;     for (int j = 0; j < 8; ++j) sT[(ck * 8 + j) * 72 + row] = f2bf(x1[j] * vv[j]);
;   }
;   __syncthreads();
;   bf16_t* uT = (bf16_t*)(p.hbuf + HB_UT);
; #pragma unroll
;   for (int i = 0; i < 2; ++i) {
;     int row = (tid >> 3) + 32 * i, ck = tid & 7;
;     *(u32x4*)(uT + ((size_t)(ct * 64 + row) * 8 + b) * 4096 + st * 64 + ck * 8) = *(const u32x4*)(sT + row * 72 + ck * 8);
;   }
	ds_read_b128 v[232:235], v220 offset:9216
	ds_read_b128 v[236:239], v220 offset:13824
	s_waitcnt lgkmcnt(1)
	global_store_dwordx4 v[198:199], v[232:235], off
	s_waitcnt lgkmcnt(0)
	global_store_dwordx4 v[210:211], v[236:239], off
	v_lshl_add_u64 v[198:199], v[198:199], 0, s[50:51]
	v_lshl_add_u64 v[210:211], v[210:211], 0, s[50:51]
	global_load_dwordx4 v[48:51], v[192:193], off offset:-4096
	global_load_dwordx4 v[52:55], v[192:193], off offset:-3072
	global_load_dwordx4 v[56:59], v[192:193], off offset:-1024
	global_load_dwordx4 v[60:63], v[192:193], off offset:0
	global_load_dwordx4 v[64:67], v[192:193], off offset:2048
	global_load_dwordx4 v[68:71], v[192:193], off offset:3072
	global_load_dwordx4 v[72:75], v[194:195], off offset:-4096
	global_load_dwordx4 v[76:79], v[194:195], off offset:-3072
	global_load_dwordx4 v[80:83], v[194:195], off offset:-1024
	global_load_dwordx4 v[84:87], v[194:195], off offset:0
	global_load_dwordx4 v[88:91], v[194:195], off offset:2048
	global_load_dwordx4 v[92:95], v[194:195], off offset:3072
	v_lshl_add_u64 v[192:193], v[192:193], 0, s[48:49]
	v_lshl_add_u64 v[194:195], v[194:195], 0, s[48:49]
	s_waitcnt vmcnt(14)
	v_cndmask_b32_e64 v0, 0, v0, s[44:45]
	v_cndmask_b32_e64 v1, 0, v1, s[44:45]
	v_cndmask_b32_e64 v2, 0, v2, s[44:45]
	v_cndmask_b32_e64 v3, 0, v3, s[44:45]
	v_cndmask_b32_e64 v4, 0, v4, s[44:45]
	v_cndmask_b32_e64 v5, 0, v5, s[44:45]
	v_cndmask_b32_e64 v6, 0, v6, s[44:45]
	v_cndmask_b32_e64 v7, 0, v7, s[44:45]
	v_lshlrev_b32_e32 v228, 16, v0
	v_and_b32_e32 v229, 0xffff0000, v0
	v_pk_fma_f32 v[224:225], v[96:97], v[228:229], 0 op_sel_hi:[1,1,0]
	v_lshlrev_b32_e32 v228, 16, v8
	v_and_b32_e32 v229, 0xffff0000, v8
	v_pk_fma_f32 v[224:225], v[112:113], v[228:229], v[224:225]
	v_lshlrev_b32_e32 v228, 16, v16
	v_and_b32_e32 v229, 0xffff0000, v16
	v_pk_fma_f32 v[224:225], v[128:129], v[228:229], v[224:225]
	v_lshlrev_b32_e32 v228, 16, v4
	v_and_b32_e32 v229, 0xffff0000, v4
	v_pk_fma_f32 v[226:227], v[104:105], v[228:229], 0 op_sel_hi:[1,1,0]
	v_lshlrev_b32_e32 v228, 16, v12
	v_and_b32_e32 v229, 0xffff0000, v12
	v_pk_fma_f32 v[226:227], v[120:121], v[228:229], v[226:227]
	v_lshlrev_b32_e32 v228, 16, v20
	v_and_b32_e32 v229, 0xffff0000, v20
	v_pk_fma_f32 v[226:227], v[136:137], v[228:229], v[226:227]
	v_pk_mul_f32 v[224:225], v[224:225], v[226:227]
	v_cvt_pk_bf16_f32 v230, v224, v225
	ds_write_b16 v219, v230
	ds_write_b16_d16_hi v219, v230 offset:144
	v_lshlrev_b32_e32 v228, 16, v1
	v_and_b32_e32 v229, 0xffff0000, v1
	v_pk_fma_f32 v[224:225], v[98:99], v[228:229], 0 op_sel_hi:[1,1,0]
	v_lshlrev_b32_e32 v228, 16, v9
	v_and_b32_e32 v229, 0xffff0000, v9
	v_pk_fma_f32 v[224:225], v[114:115], v[228:229], v[224:225]
	v_lshlrev_b32_e32 v228, 16, v17
	v_and_b32_e32 v229, 0xffff0000, v17
	v_pk_fma_f32 v[224:225], v[130:131], v[228:229], v[224:225]
	v_lshlrev_b32_e32 v228, 16, v5
	v_and_b32_e32 v229, 0xffff0000, v5
	v_pk_fma_f32 v[226:227], v[106:107], v[228:229], 0 op_sel_hi:[1,1,0]
	v_lshlrev_b32_e32 v228, 16, v13
	v_and_b32_e32 v229, 0xffff0000, v13
	v_pk_fma_f32 v[226:227], v[122:123], v[228:229], v[226:227]
	v_lshlrev_b32_e32 v228, 16, v21
	v_and_b32_e32 v229, 0xffff0000, v21
	v_pk_fma_f32 v[226:227], v[138:139], v[228:229], v[226:227]
	v_pk_mul_f32 v[224:225], v[224:225], v[226:227]
	v_cvt_pk_bf16_f32 v230, v224, v225
	ds_write_b16 v219, v230 offset:288
	ds_write_b16_d16_hi v219, v230 offset:432
	v_lshlrev_b32_e32 v228, 16, v2
	v_and_b32_e32 v229, 0xffff0000, v2
	v_pk_fma_f32 v[224:225], v[100:101], v[228:229], 0 op_sel_hi:[1,1,0]
	v_lshlrev_b32_e32 v228, 16, v10
	v_and_b32_e32 v229, 0xffff0000, v10
	v_pk_fma_f32 v[224:225], v[116:117], v[228:229], v[224:225]
	v_lshlrev_b32_e32 v228, 16, v18
	v_and_b32_e32 v229, 0xffff0000, v18
	v_pk_fma_f32 v[224:225], v[132:133], v[228:229], v[224:225]
	v_lshlrev_b32_e32 v228, 16, v6
	v_and_b32_e32 v229, 0xffff0000, v6
	v_pk_fma_f32 v[226:227], v[108:109], v[228:229], 0 op_sel_hi:[1,1,0]
	v_lshlrev_b32_e32 v228, 16, v14
	v_and_b32_e32 v229, 0xffff0000, v14
	v_pk_fma_f32 v[226:227], v[124:125], v[228:229], v[226:227]
	v_lshlrev_b32_e32 v228, 16, v22
	v_and_b32_e32 v229, 0xffff0000, v22
	v_pk_fma_f32 v[226:227], v[140:141], v[228:229], v[226:227]
	v_pk_mul_f32 v[224:225], v[224:225], v[226:227]
	v_cvt_pk_bf16_f32 v230, v224, v225
	ds_write_b16 v219, v230 offset:576
	ds_write_b16_d16_hi v219, v230 offset:720
	v_lshlrev_b32_e32 v228, 16, v3
	v_and_b32_e32 v229, 0xffff0000, v3
	v_pk_fma_f32 v[224:225], v[102:103], v[228:229], 0 op_sel_hi:[1,1,0]
	v_lshlrev_b32_e32 v228, 16, v11
	v_and_b32_e32 v229, 0xffff0000, v11
	v_pk_fma_f32 v[224:225], v[118:119], v[228:229], v[224:225]
	v_lshlrev_b32_e32 v228, 16, v19
	v_and_b32_e32 v229, 0xffff0000, v19
	v_pk_fma_f32 v[224:225], v[134:135], v[228:229], v[224:225]
	v_lshlrev_b32_e32 v228, 16, v7
	v_and_b32_e32 v229, 0xffff0000, v7
	v_pk_fma_f32 v[226:227], v[110:111], v[228:229], 0 op_sel_hi:[1,1,0]
	v_lshlrev_b32_e32 v228, 16, v15
	v_and_b32_e32 v229, 0xffff0000, v15
	v_pk_fma_f32 v[226:227], v[126:127], v[228:229], v[226:227]
	v_lshlrev_b32_e32 v228, 16, v23
	v_and_b32_e32 v229, 0xffff0000, v23
	v_pk_fma_f32 v[226:227], v[142:143], v[228:229], v[226:227]
	v_pk_mul_f32 v[224:225], v[224:225], v[226:227]
	v_cvt_pk_bf16_f32 v230, v224, v225
	ds_write_b16 v219, v230 offset:864
	ds_write_b16_d16_hi v219, v230 offset:1008
	v_cndmask_b32_e64 v40, 0, v40, s[46:47]
	v_cndmask_b32_e64 v41, 0, v41, s[46:47]
	v_cndmask_b32_e64 v42, 0, v42, s[46:47]
	v_cndmask_b32_e64 v43, 0, v43, s[46:47]
	v_cndmask_b32_e64 v44, 0, v44, s[46:47]
	v_cndmask_b32_e64 v45, 0, v45, s[46:47]
	v_cndmask_b32_e64 v46, 0, v46, s[46:47]
	v_cndmask_b32_e64 v47, 0, v47, s[46:47]
; DI float bflo(unsigned u) { return __uint_as_float(u << 16); }
; DI float bfhi(unsigned u) { return __uint_as_float(u & 0xffff0000u); }
; DI bf16_t f2bf(float x) { return (bf16_t)(pack2(x, 0.f) & 0xffffu); }
; DI void hyena_pre_tile(const Params& p, int item, char* smem) {
;     ...
;     float x1[8], vv[8];
; #pragma unroll
;     for (int j = 0; j < 8; ++j) { x1[j] = 0.f; vv[j] = 0.f; }
; #pragma unroll
;     for (int d = -1; d <= 1; ++d) {
;       int ss = s + d;
;       if (ss >= 0 && ss < 4096) {
;         u32x4 a = ldg16(HY + (size_t)ss * 1536 + 512 + c), bb = ldg16(HY + (size_t)ss * 1536 + 1024 + c);
;         float wa[8], wb[8]; ld8f(p.c_short + (d + 1) * 1536 + 512 + c, wa); ld8f(p.c_short + (d + 1) * 1536 + 1024 + c, wb);
; #pragma unroll
;         for (int q = 0; q < 4; ++q) {
;           x1[2 * q] += wa[2 * q] * bflo(a[q]); x1[2 * q + 1] += wa[2 * q + 1] * bfhi(a[q]);
;           vv[2 * q] += wb[2 * q] * bflo(bb[q]); vv[2 * q + 1] += wb[2 * q + 1] * bfhi(bb[q]);
;         }
;       }
;     }
; #pragma unroll
;     for (int j = 0; j < 8; ++j) sT[(ck * 8 + j) * 72 + row] = f2bf(x1[j] * vv[j]);
;   }
;   __syncthreads();
;   bf16_t* uT = (bf16_t*)(p.hbuf + HB_UT);
; #pragma unroll
;   for (int i = 0; i < 2; ++i) {
;     int row = (tid >> 3) + 32 * i, ck = tid & 7;
;     *(u32x4*)(uT + ((size_t)(ct * 64 + row) * 8 + b) * 4096 + st * 64 + ck * 8) = *(const u32x4*)(sT + row * 72 + ck * 8);
;   }
	v_lshlrev_b32_e32 v228, 16, v24
	v_and_b32_e32 v229, 0xffff0000, v24
	v_pk_fma_f32 v[224:225], v[96:97], v[228:229], 0 op_sel_hi:[1,1,0]
	v_lshlrev_b32_e32 v228, 16, v32
	v_and_b32_e32 v229, 0xffff0000, v32
	v_pk_fma_f32 v[224:225], v[112:113], v[228:229], v[224:225]
	v_lshlrev_b32_e32 v228, 16, v40
	v_and_b32_e32 v229, 0xffff0000, v40
	v_pk_fma_f32 v[224:225], v[128:129], v[228:229], v[224:225]
	v_lshlrev_b32_e32 v228, 16, v28
	v_and_b32_e32 v229, 0xffff0000, v28
	v_pk_fma_f32 v[226:227], v[104:105], v[228:229], 0 op_sel_hi:[1,1,0]
	v_lshlrev_b32_e32 v228, 16, v36
	v_and_b32_e32 v229, 0xffff0000, v36
	v_pk_fma_f32 v[226:227], v[120:121], v[228:229], v[226:227]
	v_lshlrev_b32_e32 v228, 16, v44
	v_and_b32_e32 v229, 0xffff0000, v44
	v_pk_fma_f32 v[226:227], v[136:137], v[228:229], v[226:227]
	v_pk_mul_f32 v[224:225], v[224:225], v[226:227]
	v_cvt_pk_bf16_f32 v230, v224, v225
	ds_write_b16 v219, v230 offset:64
	ds_write_b16_d16_hi v219, v230 offset:208
	v_lshlrev_b32_e32 v228, 16, v25
	v_and_b32_e32 v229, 0xffff0000, v25
	v_pk_fma_f32 v[224:225], v[98:99], v[228:229], 0 op_sel_hi:[1,1,0]
	v_lshlrev_b32_e32 v228, 16, v33
	v_and_b32_e32 v229, 0xffff0000, v33
	v_pk_fma_f32 v[224:225], v[114:115], v[228:229], v[224:225]
	v_lshlrev_b32_e32 v228, 16, v41
	v_and_b32_e32 v229, 0xffff0000, v41
	v_pk_fma_f32 v[224:225], v[130:131], v[228:229], v[224:225]
	v_lshlrev_b32_e32 v228, 16, v29
	v_and_b32_e32 v229, 0xffff0000, v29
	v_pk_fma_f32 v[226:227], v[106:107], v[228:229], 0 op_sel_hi:[1,1,0]
	v_lshlrev_b32_e32 v228, 16, v37
	v_and_b32_e32 v229, 0xffff0000, v37
	v_pk_fma_f32 v[226:227], v[122:123], v[228:229], v[226:227]
	v_lshlrev_b32_e32 v228, 16, v45
	v_and_b32_e32 v229, 0xffff0000, v45
	v_pk_fma_f32 v[226:227], v[138:139], v[228:229], v[226:227]
	v_pk_mul_f32 v[224:225], v[224:225], v[226:227]
	v_cvt_pk_bf16_f32 v230, v224, v225
	ds_write_b16 v219, v230 offset:352
	ds_write_b16_d16_hi v219, v230 offset:496
	v_lshlrev_b32_e32 v228, 16, v26
	v_and_b32_e32 v229, 0xffff0000, v26
	v_pk_fma_f32 v[224:225], v[100:101], v[228:229], 0 op_sel_hi:[1,1,0]
	v_lshlrev_b32_e32 v228, 16, v34
	v_and_b32_e32 v229, 0xffff0000, v34
	v_pk_fma_f32 v[224:225], v[116:117], v[228:229], v[224:225]
	v_lshlrev_b32_e32 v228, 16, v42
	v_and_b32_e32 v229, 0xffff0000, v42
	v_pk_fma_f32 v[224:225], v[132:133], v[228:229], v[224:225]
	v_lshlrev_b32_e32 v228, 16, v30
	v_and_b32_e32 v229, 0xffff0000, v30
	v_pk_fma_f32 v[226:227], v[108:109], v[228:229], 0 op_sel_hi:[1,1,0]
	v_lshlrev_b32_e32 v228, 16, v38
	v_and_b32_e32 v229, 0xffff0000, v38
	v_pk_fma_f32 v[226:227], v[124:125], v[228:229], v[226:227]
	v_lshlrev_b32_e32 v228, 16, v46
	v_and_b32_e32 v229, 0xffff0000, v46
	v_pk_fma_f32 v[226:227], v[140:141], v[228:229], v[226:227]
	v_pk_mul_f32 v[224:225], v[224:225], v[226:227]
	v_cvt_pk_bf16_f32 v230, v224, v225
	ds_write_b16 v219, v230 offset:640
	ds_write_b16_d16_hi v219, v230 offset:784
	v_lshlrev_b32_e32 v228, 16, v27
	v_and_b32_e32 v229, 0xffff0000, v27
	v_pk_fma_f32 v[224:225], v[102:103], v[228:229], 0 op_sel_hi:[1,1,0]
	v_lshlrev_b32_e32 v228, 16, v35
	v_and_b32_e32 v229, 0xffff0000, v35
	v_pk_fma_f32 v[224:225], v[118:119], v[228:229], v[224:225]
	v_lshlrev_b32_e32 v228, 16, v43
	v_and_b32_e32 v229, 0xffff0000, v43
	v_pk_fma_f32 v[224:225], v[134:135], v[228:229], v[224:225]
	v_lshlrev_b32_e32 v228, 16, v31
	v_and_b32_e32 v229, 0xffff0000, v31
	v_pk_fma_f32 v[226:227], v[110:111], v[228:229], 0 op_sel_hi:[1,1,0]
	v_lshlrev_b32_e32 v228, 16, v39
	v_and_b32_e32 v229, 0xffff0000, v39
	v_pk_fma_f32 v[226:227], v[126:127], v[228:229], v[226:227]
	v_lshlrev_b32_e32 v228, 16, v47
	v_and_b32_e32 v229, 0xffff0000, v47
	v_pk_fma_f32 v[226:227], v[142:143], v[228:229], v[226:227]
	v_pk_mul_f32 v[224:225], v[224:225], v[226:227]
	v_cvt_pk_bf16_f32 v230, v224, v225
	ds_write_b16 v219, v230 offset:928
	ds_write_b16_d16_hi v219, v230 offset:1072
	s_waitcnt lgkmcnt(0)
	s_barrier
	ds_read_b128 v[232:235], v220
	ds_read_b128 v[236:239], v220 offset:4608
	s_waitcnt lgkmcnt(1)
	global_store_dwordx4 v[198:199], v[232:235], off
	s_waitcnt lgkmcnt(0)
	global_store_dwordx4 v[210:211], v[236:239], off
	v_lshl_add_u64 v[198:199], v[198:199], 0, s[50:51]
	v_lshl_add_u64 v[210:211], v[210:211], 0, s[50:51]
	global_load_dwordx4 v[0:3], v[192:193], off offset:-4096
	global_load_dwordx4 v[4:7], v[192:193], off offset:-3072
	global_load_dwordx4 v[8:11], v[192:193], off offset:-1024
	global_load_dwordx4 v[12:15], v[192:193], off offset:0
	global_load_dwordx4 v[16:19], v[192:193], off offset:2048
	global_load_dwordx4 v[20:23], v[192:193], off offset:3072
	global_load_dwordx4 v[24:27], v[194:195], off offset:-4096
	global_load_dwordx4 v[28:31], v[194:195], off offset:-3072
	global_load_dwordx4 v[32:35], v[194:195], off offset:-1024
	global_load_dwordx4 v[36:39], v[194:195], off offset:0
	global_load_dwordx4 v[40:43], v[194:195], off offset:2048
	global_load_dwordx4 v[44:47], v[194:195], off offset:3072
	v_lshl_add_u64 v[192:193], v[192:193], 0, s[48:49]
	v_lshl_add_u64 v[194:195], v[194:195], 0, s[48:49]
	s_waitcnt vmcnt(14)
; DI float bflo(unsigned u) { return __uint_as_float(u << 16); }
; DI float bfhi(unsigned u) { return __uint_as_float(u & 0xffff0000u); }
; DI bf16_t f2bf(float x) { return (bf16_t)(pack2(x, 0.f) & 0xffffu); }
; DI void hyena_pre_tile(const Params& p, int item, char* smem) {
;     ...
;     float x1[8], vv[8];
; #pragma unroll
;     for (int j = 0; j < 8; ++j) { x1[j] = 0.f; vv[j] = 0.f; }
; #pragma unroll
;     for (int d = -1; d <= 1; ++d) {
;       int ss = s + d;
;       if (ss >= 0 && ss < 4096) {
;         u32x4 a = ldg16(HY + (size_t)ss * 1536 + 512 + c), bb = ldg16(HY + (size_t)ss * 1536 + 1024 + c);
;         float wa[8], wb[8]; ld8f(p.c_short + (d + 1) * 1536 + 512 + c, wa); ld8f(p.c_short + (d + 1) * 1536 + 1024 + c, wb);
; #pragma unroll
;         for (int q = 0; q < 4; ++q) {
;           x1[2 * q] += wa[2 * q] * bflo(a[q]); x1[2 * q + 1] += wa[2 * q + 1] * bfhi(a[q]);
;           vv[2 * q] += wb[2 * q] * bflo(bb[q]); vv[2 * q + 1] += wb[2 * q + 1] * bfhi(bb[q]);
;         }
;       }
;     }
; #pragma unroll
;     for (int j = 0; j < 8; ++j) sT[(ck * 8 + j) * 72 + row] = f2bf(x1[j] * vv[j]);
	v_cndmask_b32_e64 v48, 0, v48, s[44:45]
	v_cndmask_b32_e64 v49, 0, v49, s[44:45]
	v_cndmask_b32_e64 v50, 0, v50, s[44:45]
	v_cndmask_b32_e64 v51, 0, v51, s[44:45]
	v_cndmask_b32_e64 v52, 0, v52, s[44:45]
	v_cndmask_b32_e64 v53, 0, v53, s[44:45]
	v_cndmask_b32_e64 v54, 0, v54, s[44:45]
	v_cndmask_b32_e64 v55, 0, v55, s[44:45]
	v_lshlrev_b32_e32 v228, 16, v48
	v_and_b32_e32 v229, 0xffff0000, v48
	v_pk_fma_f32 v[224:225], v[96:97], v[228:229], 0 op_sel_hi:[1,1,0]
	v_lshlrev_b32_e32 v228, 16, v56
	v_and_b32_e32 v229, 0xffff0000, v56
	v_pk_fma_f32 v[224:225], v[112:113], v[228:229], v[224:225]
	v_lshlrev_b32_e32 v228, 16, v64
	v_and_b32_e32 v229, 0xffff0000, v64
	v_pk_fma_f32 v[224:225], v[128:129], v[228:229], v[224:225]
	v_lshlrev_b32_e32 v228, 16, v52
	v_and_b32_e32 v229, 0xffff0000, v52
	v_pk_fma_f32 v[226:227], v[104:105], v[228:229], 0 op_sel_hi:[1,1,0]
	v_lshlrev_b32_e32 v228, 16, v60
	v_and_b32_e32 v229, 0xffff0000, v60
	v_pk_fma_f32 v[226:227], v[120:121], v[228:229], v[226:227]
	v_lshlrev_b32_e32 v228, 16, v68
	v_and_b32_e32 v229, 0xffff0000, v68
	v_pk_fma_f32 v[226:227], v[136:137], v[228:229], v[226:227]
	v_pk_mul_f32 v[224:225], v[224:225], v[226:227]
	v_cvt_pk_bf16_f32 v230, v224, v225
	ds_write_b16 v219, v230 offset:9216
	ds_write_b16_d16_hi v219, v230 offset:9360
	v_lshlrev_b32_e32 v228, 16, v49
	v_and_b32_e32 v229, 0xffff0000, v49
	v_pk_fma_f32 v[224:225], v[98:99], v[228:229], 0 op_sel_hi:[1,1,0]
	v_lshlrev_b32_e32 v228, 16, v57
	v_and_b32_e32 v229, 0xffff0000, v57
	v_pk_fma_f32 v[224:225], v[114:115], v[228:229], v[224:225]
	v_lshlrev_b32_e32 v228, 16, v65
	v_and_b32_e32 v229, 0xffff0000, v65
	v_pk_fma_f32 v[224:225], v[130:131], v[228:229], v[224:225]
	v_lshlrev_b32_e32 v228, 16, v53
	v_and_b32_e32 v229, 0xffff0000, v53
	v_pk_fma_f32 v[226:227], v[106:107], v[228:229], 0 op_sel_hi:[1,1,0]
	v_lshlrev_b32_e32 v228, 16, v61
	v_and_b32_e32 v229, 0xffff0000, v61
	v_pk_fma_f32 v[226:227], v[122:123], v[228:229], v[226:227]
	v_lshlrev_b32_e32 v228, 16, v69
	v_and_b32_e32 v229, 0xffff0000, v69
	v_pk_fma_f32 v[226:227], v[138:139], v[228:229], v[226:227]
	v_pk_mul_f32 v[224:225], v[224:225], v[226:227]
	v_cvt_pk_bf16_f32 v230, v224, v225
	ds_write_b16 v219, v230 offset:9504
	ds_write_b16_d16_hi v219, v230 offset:9648
	v_lshlrev_b32_e32 v228, 16, v50
	v_and_b32_e32 v229, 0xffff0000, v50
	v_pk_fma_f32 v[224:225], v[100:101], v[228:229], 0 op_sel_hi:[1,1,0]
	v_lshlrev_b32_e32 v228, 16, v58
	v_and_b32_e32 v229, 0xffff0000, v58
	v_pk_fma_f32 v[224:225], v[116:117], v[228:229], v[224:225]
	v_lshlrev_b32_e32 v228, 16, v66
	v_and_b32_e32 v229, 0xffff0000, v66
	v_pk_fma_f32 v[224:225], v[132:133], v[228:229], v[224:225]
	v_lshlrev_b32_e32 v228, 16, v54
	v_and_b32_e32 v229, 0xffff0000, v54
	v_pk_fma_f32 v[226:227], v[108:109], v[228:229], 0 op_sel_hi:[1,1,0]
	v_lshlrev_b32_e32 v228, 16, v62
	v_and_b32_e32 v229, 0xffff0000, v62
	v_pk_fma_f32 v[226:227], v[124:125], v[228:229], v[226:227]
	v_lshlrev_b32_e32 v228, 16, v70
	v_and_b32_e32 v229, 0xffff0000, v70
	v_pk_fma_f32 v[226:227], v[140:141], v[228:229], v[226:227]
	v_pk_mul_f32 v[224:225], v[224:225], v[226:227]
	v_cvt_pk_bf16_f32 v230, v224, v225
	ds_write_b16 v219, v230 offset:9792
	ds_write_b16_d16_hi v219, v230 offset:9936
	v_lshlrev_b32_e32 v228, 16, v51
	v_and_b32_e32 v229, 0xffff0000, v51
	v_pk_fma_f32 v[224:225], v[102:103], v[228:229], 0 op_sel_hi:[1,1,0]
	v_lshlrev_b32_e32 v228, 16, v59
	v_and_b32_e32 v229, 0xffff0000, v59
	v_pk_fma_f32 v[224:225], v[118:119], v[228:229], v[224:225]
	v_lshlrev_b32_e32 v228, 16, v67
	v_and_b32_e32 v229, 0xffff0000, v67
	v_pk_fma_f32 v[224:225], v[134:135], v[228:229], v[224:225]
	v_lshlrev_b32_e32 v228, 16, v55
	v_and_b32_e32 v229, 0xffff0000, v55
	v_pk_fma_f32 v[226:227], v[110:111], v[228:229], 0 op_sel_hi:[1,1,0]
	v_lshlrev_b32_e32 v228, 16, v63
	v_and_b32_e32 v229, 0xffff0000, v63
	v_pk_fma_f32 v[226:227], v[126:127], v[228:229], v[226:227]
	v_lshlrev_b32_e32 v228, 16, v71
	v_and_b32_e32 v229, 0xffff0000, v71
	v_pk_fma_f32 v[226:227], v[142:143], v[228:229], v[226:227]
	v_pk_mul_f32 v[224:225], v[224:225], v[226:227]
	v_cvt_pk_bf16_f32 v230, v224, v225
	ds_write_b16 v219, v230 offset:10080
	ds_write_b16_d16_hi v219, v230 offset:10224
	v_cndmask_b32_e64 v88, 0, v88, s[46:47]
	v_cndmask_b32_e64 v89, 0, v89, s[46:47]
	v_cndmask_b32_e64 v90, 0, v90, s[46:47]
	v_cndmask_b32_e64 v91, 0, v91, s[46:47]
	v_cndmask_b32_e64 v92, 0, v92, s[46:47]
	v_cndmask_b32_e64 v93, 0, v93, s[46:47]
	v_cndmask_b32_e64 v94, 0, v94, s[46:47]
	v_cndmask_b32_e64 v95, 0, v95, s[46:47]
	v_lshlrev_b32_e32 v228, 16, v72
	v_and_b32_e32 v229, 0xffff0000, v72
	v_pk_fma_f32 v[224:225], v[96:97], v[228:229], 0 op_sel_hi:[1,1,0]
	v_lshlrev_b32_e32 v228, 16, v80
	v_and_b32_e32 v229, 0xffff0000, v80
	v_pk_fma_f32 v[224:225], v[112:113], v[228:229], v[224:225]
	v_lshlrev_b32_e32 v228, 16, v88
	v_and_b32_e32 v229, 0xffff0000, v88
	v_pk_fma_f32 v[224:225], v[128:129], v[228:229], v[224:225]
	v_lshlrev_b32_e32 v228, 16, v76
	v_and_b32_e32 v229, 0xffff0000, v76
	v_pk_fma_f32 v[226:227], v[104:105], v[228:229], 0 op_sel_hi:[1,1,0]
	v_lshlrev_b32_e32 v228, 16, v84
	v_and_b32_e32 v229, 0xffff0000, v84
	v_pk_fma_f32 v[226:227], v[120:121], v[228:229], v[226:227]
	v_lshlrev_b32_e32 v228, 16, v92
	v_and_b32_e32 v229, 0xffff0000, v92
	v_pk_fma_f32 v[226:227], v[136:137], v[228:229], v[226:227]
	v_pk_mul_f32 v[224:225], v[224:225], v[226:227]
	v_cvt_pk_bf16_f32 v230, v224, v225
	ds_write_b16 v219, v230 offset:9280
	ds_write_b16_d16_hi v219, v230 offset:9424
	v_lshlrev_b32_e32 v228, 16, v73
	v_and_b32_e32 v229, 0xffff0000, v73
	v_pk_fma_f32 v[224:225], v[98:99], v[228:229], 0 op_sel_hi:[1,1,0]
; DI float bflo(unsigned u) { return __uint_as_float(u << 16); }
; DI float bfhi(unsigned u) { return __uint_as_float(u & 0xffff0000u); }
; DI bf16_t f2bf(float x) { return (bf16_t)(pack2(x, 0.f) & 0xffffu); }
; DI void hyena_pre_tile(const Params& p, int item, char* smem) {
;     ...
;     float x1[8], vv[8];
; #pragma unroll
;     for (int j = 0; j < 8; ++j) { x1[j] = 0.f; vv[j] = 0.f; }
; #pragma unroll
;     for (int d = -1; d <= 1; ++d) {
;       int ss = s + d;
;       if (ss >= 0 && ss < 4096) {
;         u32x4 a = ldg16(HY + (size_t)ss * 1536 + 512 + c), bb = ldg16(HY + (size_t)ss * 1536 + 1024 + c);
;         float wa[8], wb[8]; ld8f(p.c_short + (d + 1) * 1536 + 512 + c, wa); ld8f(p.c_short + (d + 1) * 1536 + 1024 + c, wb);
; #pragma unroll
;         for (int q = 0; q < 4; ++q) {
;           x1[2 * q] += wa[2 * q] * bflo(a[q]); x1[2 * q + 1] += wa[2 * q + 1] * bfhi(a[q]);
;           vv[2 * q] += wb[2 * q] * bflo(bb[q]); vv[2 * q + 1] += wb[2 * q + 1] * bfhi(bb[q]);
;         }
;       }
;     }
; #pragma unroll
;     for (int j = 0; j < 8; ++j) sT[(ck * 8 + j) * 72 + row] = f2bf(x1[j] * vv[j]);
;   }
;   __syncthreads();
;   bf16_t* uT = (bf16_t*)(p.hbuf + HB_UT);
; #pragma unroll
;   for (int i = 0; i < 2; ++i) {
;     int row = (tid >> 3) + 32 * i, ck = tid & 7;
;     *(u32x4*)(uT + ((size_t)(ct * 64 + row) * 8 + b) * 4096 + st * 64 + ck * 8) = *(const u32x4*)(sT + row * 72 + ck * 8);
;   }
	v_lshlrev_b32_e32 v228, 16, v81
	v_and_b32_e32 v229, 0xffff0000, v81
	v_pk_fma_f32 v[224:225], v[114:115], v[228:229], v[224:225]
	v_lshlrev_b32_e32 v228, 16, v89
	v_and_b32_e32 v229, 0xffff0000, v89
	v_pk_fma_f32 v[224:225], v[130:131], v[228:229], v[224:225]
	v_lshlrev_b32_e32 v228, 16, v77
	v_and_b32_e32 v229, 0xffff0000, v77
	v_pk_fma_f32 v[226:227], v[106:107], v[228:229], 0 op_sel_hi:[1,1,0]
	v_lshlrev_b32_e32 v228, 16, v85
	v_and_b32_e32 v229, 0xffff0000, v85
	v_pk_fma_f32 v[226:227], v[122:123], v[228:229], v[226:227]
	v_lshlrev_b32_e32 v228, 16, v93
	v_and_b32_e32 v229, 0xffff0000, v93
	v_pk_fma_f32 v[226:227], v[138:139], v[228:229], v[226:227]
	v_pk_mul_f32 v[224:225], v[224:225], v[226:227]
	v_cvt_pk_bf16_f32 v230, v224, v225
	ds_write_b16 v219, v230 offset:9568
	ds_write_b16_d16_hi v219, v230 offset:9712
	v_lshlrev_b32_e32 v228, 16, v74
	v_and_b32_e32 v229, 0xffff0000, v74
	v_pk_fma_f32 v[224:225], v[100:101], v[228:229], 0 op_sel_hi:[1,1,0]
	v_lshlrev_b32_e32 v228, 16, v82
	v_and_b32_e32 v229, 0xffff0000, v82
	v_pk_fma_f32 v[224:225], v[116:117], v[228:229], v[224:225]
	v_lshlrev_b32_e32 v228, 16, v90
	v_and_b32_e32 v229, 0xffff0000, v90
	v_pk_fma_f32 v[224:225], v[132:133], v[228:229], v[224:225]
	v_lshlrev_b32_e32 v228, 16, v78
	v_and_b32_e32 v229, 0xffff0000, v78
	v_pk_fma_f32 v[226:227], v[108:109], v[228:229], 0 op_sel_hi:[1,1,0]
	v_lshlrev_b32_e32 v228, 16, v86
	v_and_b32_e32 v229, 0xffff0000, v86
	v_pk_fma_f32 v[226:227], v[124:125], v[228:229], v[226:227]
	v_lshlrev_b32_e32 v228, 16, v94
	v_and_b32_e32 v229, 0xffff0000, v94
	v_pk_fma_f32 v[226:227], v[140:141], v[228:229], v[226:227]
	v_pk_mul_f32 v[224:225], v[224:225], v[226:227]
	v_cvt_pk_bf16_f32 v230, v224, v225
	ds_write_b16 v219, v230 offset:9856
	ds_write_b16_d16_hi v219, v230 offset:10000
	v_lshlrev_b32_e32 v228, 16, v75
	v_and_b32_e32 v229, 0xffff0000, v75
	v_pk_fma_f32 v[224:225], v[102:103], v[228:229], 0 op_sel_hi:[1,1,0]
	v_lshlrev_b32_e32 v228, 16, v83
	v_and_b32_e32 v229, 0xffff0000, v83
	v_pk_fma_f32 v[224:225], v[118:119], v[228:229], v[224:225]
	v_lshlrev_b32_e32 v228, 16, v91
	v_and_b32_e32 v229, 0xffff0000, v91
	v_pk_fma_f32 v[224:225], v[134:135], v[228:229], v[224:225]
	v_lshlrev_b32_e32 v228, 16, v79
	v_and_b32_e32 v229, 0xffff0000, v79
	v_pk_fma_f32 v[226:227], v[110:111], v[228:229], 0 op_sel_hi:[1,1,0]
	v_lshlrev_b32_e32 v228, 16, v87
	v_and_b32_e32 v229, 0xffff0000, v87
	v_pk_fma_f32 v[226:227], v[126:127], v[228:229], v[226:227]
	v_lshlrev_b32_e32 v228, 16, v95
	v_and_b32_e32 v229, 0xffff0000, v95
	v_pk_fma_f32 v[226:227], v[142:143], v[228:229], v[226:227]
	v_pk_mul_f32 v[224:225], v[224:225], v[226:227]
	v_cvt_pk_bf16_f32 v230, v224, v225
	ds_write_b16 v219, v230 offset:10144
	ds_write_b16_d16_hi v219, v230 offset:10288
	s_waitcnt lgkmcnt(0)
	s_barrier
	ds_read_b128 v[232:235], v220 offset:9216
	ds_read_b128 v[236:239], v220 offset:13824
	s_waitcnt lgkmcnt(1)
	global_store_dwordx4 v[198:199], v[232:235], off
	s_waitcnt lgkmcnt(0)
	global_store_dwordx4 v[210:211], v[236:239], off
	v_lshl_add_u64 v[198:199], v[198:199], 0, s[50:51]
	v_lshl_add_u64 v[210:211], v[210:211], 0, s[50:51]
	global_load_dwordx4 v[48:51], v[192:193], off offset:-4096
	global_load_dwordx4 v[52:55], v[192:193], off offset:-3072
	global_load_dwordx4 v[56:59], v[192:193], off offset:-1024
	global_load_dwordx4 v[60:63], v[192:193], off offset:0
	global_load_dwordx4 v[64:67], v[192:193], off offset:2048
	global_load_dwordx4 v[68:71], v[192:193], off offset:3072
	global_load_dwordx4 v[72:75], v[194:195], off offset:-4096
	global_load_dwordx4 v[76:79], v[194:195], off offset:-3072
	global_load_dwordx4 v[80:83], v[194:195], off offset:-1024
	global_load_dwordx4 v[84:87], v[194:195], off offset:0
	global_load_dwordx4 v[88:91], v[194:195], off offset:2048
	global_load_dwordx4 v[92:95], v[194:195], off offset:3072
	v_lshl_add_u64 v[192:193], v[192:193], 0, s[48:49]
	v_lshl_add_u64 v[194:195], v[194:195], 0, s[48:49]
	s_waitcnt vmcnt(14)
	v_cndmask_b32_e64 v0, 0, v0, s[44:45]
	v_cndmask_b32_e64 v1, 0, v1, s[44:45]
	v_cndmask_b32_e64 v2, 0, v2, s[44:45]
	v_cndmask_b32_e64 v3, 0, v3, s[44:45]
	v_cndmask_b32_e64 v4, 0, v4, s[44:45]
	v_cndmask_b32_e64 v5, 0, v5, s[44:45]
	v_cndmask_b32_e64 v6, 0, v6, s[44:45]
	v_cndmask_b32_e64 v7, 0, v7, s[44:45]
	v_lshlrev_b32_e32 v228, 16, v0
	v_and_b32_e32 v229, 0xffff0000, v0
	v_pk_fma_f32 v[224:225], v[96:97], v[228:229], 0 op_sel_hi:[1,1,0]
	v_lshlrev_b32_e32 v228, 16, v8
	v_and_b32_e32 v229, 0xffff0000, v8
	v_pk_fma_f32 v[224:225], v[112:113], v[228:229], v[224:225]
	v_lshlrev_b32_e32 v228, 16, v16
	v_and_b32_e32 v229, 0xffff0000, v16
	v_pk_fma_f32 v[224:225], v[128:129], v[228:229], v[224:225]
	v_lshlrev_b32_e32 v228, 16, v4
	v_and_b32_e32 v229, 0xffff0000, v4
	v_pk_fma_f32 v[226:227], v[104:105], v[228:229], 0 op_sel_hi:[1,1,0]
	v_lshlrev_b32_e32 v228, 16, v12
	v_and_b32_e32 v229, 0xffff0000, v12
	v_pk_fma_f32 v[226:227], v[120:121], v[228:229], v[226:227]
	v_lshlrev_b32_e32 v228, 16, v20
	v_and_b32_e32 v229, 0xffff0000, v20
	v_pk_fma_f32 v[226:227], v[136:137], v[228:229], v[226:227]
	v_pk_mul_f32 v[224:225], v[224:225], v[226:227]
	v_cvt_pk_bf16_f32 v230, v224, v225
	ds_write_b16 v219, v230
	ds_write_b16_d16_hi v219, v230 offset:144
	v_lshlrev_b32_e32 v228, 16, v1
	v_and_b32_e32 v229, 0xffff0000, v1
	v_pk_fma_f32 v[224:225], v[98:99], v[228:229], 0 op_sel_hi:[1,1,0]
	v_lshlrev_b32_e32 v228, 16, v9
	v_and_b32_e32 v229, 0xffff0000, v9
	v_pk_fma_f32 v[224:225], v[114:115], v[228:229], v[224:225]
	v_lshlrev_b32_e32 v228, 16, v17
	v_and_b32_e32 v229, 0xffff0000, v17
	v_pk_fma_f32 v[224:225], v[130:131], v[228:229], v[224:225]
; DI float bflo(unsigned u) { return __uint_as_float(u << 16); }
; DI float bfhi(unsigned u) { return __uint_as_float(u & 0xffff0000u); }
; DI bf16_t f2bf(float x) { return (bf16_t)(pack2(x, 0.f) & 0xffffu); }
; DI void hyena_pre_tile(const Params& p, int item, char* smem) {
;     ...
;     float x1[8], vv[8];
; #pragma unroll
;     for (int j = 0; j < 8; ++j) { x1[j] = 0.f; vv[j] = 0.f; }
; #pragma unroll
;     for (int d = -1; d <= 1; ++d) {
;       int ss = s + d;
;       if (ss >= 0 && ss < 4096) {
;         u32x4 a = ldg16(HY + (size_t)ss * 1536 + 512 + c), bb = ldg16(HY + (size_t)ss * 1536 + 1024 + c);
;         float wa[8], wb[8]; ld8f(p.c_short + (d + 1) * 1536 + 512 + c, wa); ld8f(p.c_short + (d + 1) * 1536 + 1024 + c, wb);
; #pragma unroll
;         for (int q = 0; q < 4; ++q) {
;           x1[2 * q] += wa[2 * q] * bflo(a[q]); x1[2 * q + 1] += wa[2 * q + 1] * bfhi(a[q]);
;           vv[2 * q] += wb[2 * q] * bflo(bb[q]); vv[2 * q + 1] += wb[2 * q + 1] * bfhi(bb[q]);
;         }
;       }
;     }
; #pragma unroll
;     for (int j = 0; j < 8; ++j) sT[(ck * 8 + j) * 72 + row] = f2bf(x1[j] * vv[j]);
	v_lshlrev_b32_e32 v228, 16, v5
	v_and_b32_e32 v229, 0xffff0000, v5
	v_pk_fma_f32 v[226:227], v[106:107], v[228:229], 0 op_sel_hi:[1,1,0]
	v_lshlrev_b32_e32 v228, 16, v13
	v_and_b32_e32 v229, 0xffff0000, v13
	v_pk_fma_f32 v[226:227], v[122:123], v[228:229], v[226:227]
	v_lshlrev_b32_e32 v228, 16, v21
	v_and_b32_e32 v229, 0xffff0000, v21
	v_pk_fma_f32 v[226:227], v[138:139], v[228:229], v[226:227]
	v_pk_mul_f32 v[224:225], v[224:225], v[226:227]
	v_cvt_pk_bf16_f32 v230, v224, v225
	ds_write_b16 v219, v230 offset:288
	ds_write_b16_d16_hi v219, v230 offset:432
	v_lshlrev_b32_e32 v228, 16, v2
	v_and_b32_e32 v229, 0xffff0000, v2
	v_pk_fma_f32 v[224:225], v[100:101], v[228:229], 0 op_sel_hi:[1,1,0]
	v_lshlrev_b32_e32 v228, 16, v10
	v_and_b32_e32 v229, 0xffff0000, v10
	v_pk_fma_f32 v[224:225], v[116:117], v[228:229], v[224:225]
	v_lshlrev_b32_e32 v228, 16, v18
	v_and_b32_e32 v229, 0xffff0000, v18
	v_pk_fma_f32 v[224:225], v[132:133], v[228:229], v[224:225]
	v_lshlrev_b32_e32 v228, 16, v6
	v_and_b32_e32 v229, 0xffff0000, v6
	v_pk_fma_f32 v[226:227], v[108:109], v[228:229], 0 op_sel_hi:[1,1,0]
	v_lshlrev_b32_e32 v228, 16, v14
	v_and_b32_e32 v229, 0xffff0000, v14
	v_pk_fma_f32 v[226:227], v[124:125], v[228:229], v[226:227]
	v_lshlrev_b32_e32 v228, 16, v22
	v_and_b32_e32 v229, 0xffff0000, v22
	v_pk_fma_f32 v[226:227], v[140:141], v[228:229], v[226:227]
	v_pk_mul_f32 v[224:225], v[224:225], v[226:227]
	v_cvt_pk_bf16_f32 v230, v224, v225
	ds_write_b16 v219, v230 offset:576
	ds_write_b16_d16_hi v219, v230 offset:720
	v_lshlrev_b32_e32 v228, 16, v3
	v_and_b32_e32 v229, 0xffff0000, v3
	v_pk_fma_f32 v[224:225], v[102:103], v[228:229], 0 op_sel_hi:[1,1,0]
	v_lshlrev_b32_e32 v228, 16, v11
	v_and_b32_e32 v229, 0xffff0000, v11
	v_pk_fma_f32 v[224:225], v[118:119], v[228:229], v[224:225]
	v_lshlrev_b32_e32 v228, 16, v19
	v_and_b32_e32 v229, 0xffff0000, v19
	v_pk_fma_f32 v[224:225], v[134:135], v[228:229], v[224:225]
	v_lshlrev_b32_e32 v228, 16, v7
	v_and_b32_e32 v229, 0xffff0000, v7
	v_pk_fma_f32 v[226:227], v[110:111], v[228:229], 0 op_sel_hi:[1,1,0]
	v_lshlrev_b32_e32 v228, 16, v15
	v_and_b32_e32 v229, 0xffff0000, v15
	v_pk_fma_f32 v[226:227], v[126:127], v[228:229], v[226:227]
	v_lshlrev_b32_e32 v228, 16, v23
	v_and_b32_e32 v229, 0xffff0000, v23
	v_pk_fma_f32 v[226:227], v[142:143], v[228:229], v[226:227]
	v_pk_mul_f32 v[224:225], v[224:225], v[226:227]
	v_cvt_pk_bf16_f32 v230, v224, v225
	ds_write_b16 v219, v230 offset:864
	ds_write_b16_d16_hi v219, v230 offset:1008
	v_cndmask_b32_e64 v40, 0, v40, s[46:47]
	v_cndmask_b32_e64 v41, 0, v41, s[46:47]
	v_cndmask_b32_e64 v42, 0, v42, s[46:47]
	v_cndmask_b32_e64 v43, 0, v43, s[46:47]
	v_cndmask_b32_e64 v44, 0, v44, s[46:47]
	v_cndmask_b32_e64 v45, 0, v45, s[46:47]
	v_cndmask_b32_e64 v46, 0, v46, s[46:47]
	v_cndmask_b32_e64 v47, 0, v47, s[46:47]
	v_lshlrev_b32_e32 v228, 16, v24
	v_and_b32_e32 v229, 0xffff0000, v24
	v_pk_fma_f32 v[224:225], v[96:97], v[228:229], 0 op_sel_hi:[1,1,0]
	v_lshlrev_b32_e32 v228, 16, v32
	v_and_b32_e32 v229, 0xffff0000, v32
	v_pk_fma_f32 v[224:225], v[112:113], v[228:229], v[224:225]
	v_lshlrev_b32_e32 v228, 16, v40
	v_and_b32_e32 v229, 0xffff0000, v40
	v_pk_fma_f32 v[224:225], v[128:129], v[228:229], v[224:225]
	v_lshlrev_b32_e32 v228, 16, v28
	v_and_b32_e32 v229, 0xffff0000, v28
	v_pk_fma_f32 v[226:227], v[104:105], v[228:229], 0 op_sel_hi:[1,1,0]
	v_lshlrev_b32_e32 v228, 16, v36
	v_and_b32_e32 v229, 0xffff0000, v36
	v_pk_fma_f32 v[226:227], v[120:121], v[228:229], v[226:227]
	v_lshlrev_b32_e32 v228, 16, v44
	v_and_b32_e32 v229, 0xffff0000, v44
	v_pk_fma_f32 v[226:227], v[136:137], v[228:229], v[226:227]
	v_pk_mul_f32 v[224:225], v[224:225], v[226:227]
	v_cvt_pk_bf16_f32 v230, v224, v225
	ds_write_b16 v219, v230 offset:64
	ds_write_b16_d16_hi v219, v230 offset:208
	v_lshlrev_b32_e32 v228, 16, v25
	v_and_b32_e32 v229, 0xffff0000, v25
	v_pk_fma_f32 v[224:225], v[98:99], v[228:229], 0 op_sel_hi:[1,1,0]
	v_lshlrev_b32_e32 v228, 16, v33
	v_and_b32_e32 v229, 0xffff0000, v33
	v_pk_fma_f32 v[224:225], v[114:115], v[228:229], v[224:225]
	v_lshlrev_b32_e32 v228, 16, v41
	v_and_b32_e32 v229, 0xffff0000, v41
	v_pk_fma_f32 v[224:225], v[130:131], v[228:229], v[224:225]
	v_lshlrev_b32_e32 v228, 16, v29
	v_and_b32_e32 v229, 0xffff0000, v29
	v_pk_fma_f32 v[226:227], v[106:107], v[228:229], 0 op_sel_hi:[1,1,0]
	v_lshlrev_b32_e32 v228, 16, v37
	v_and_b32_e32 v229, 0xffff0000, v37
	v_pk_fma_f32 v[226:227], v[122:123], v[228:229], v[226:227]
	v_lshlrev_b32_e32 v228, 16, v45
	v_and_b32_e32 v229, 0xffff0000, v45
	v_pk_fma_f32 v[226:227], v[138:139], v[228:229], v[226:227]
	v_pk_mul_f32 v[224:225], v[224:225], v[226:227]
	v_cvt_pk_bf16_f32 v230, v224, v225
	ds_write_b16 v219, v230 offset:352
	ds_write_b16_d16_hi v219, v230 offset:496
	v_lshlrev_b32_e32 v228, 16, v26
	v_and_b32_e32 v229, 0xffff0000, v26
	v_pk_fma_f32 v[224:225], v[100:101], v[228:229], 0 op_sel_hi:[1,1,0]
	v_lshlrev_b32_e32 v228, 16, v34
	v_and_b32_e32 v229, 0xffff0000, v34
	v_pk_fma_f32 v[224:225], v[116:117], v[228:229], v[224:225]
	v_lshlrev_b32_e32 v228, 16, v42
	v_and_b32_e32 v229, 0xffff0000, v42
	v_pk_fma_f32 v[224:225], v[132:133], v[228:229], v[224:225]
	v_lshlrev_b32_e32 v228, 16, v30
	v_and_b32_e32 v229, 0xffff0000, v30
	v_pk_fma_f32 v[226:227], v[108:109], v[228:229], 0 op_sel_hi:[1,1,0]
	v_lshlrev_b32_e32 v228, 16, v38
	v_and_b32_e32 v229, 0xffff0000, v38
	v_pk_fma_f32 v[226:227], v[124:125], v[228:229], v[226:227]
	v_lshlrev_b32_e32 v228, 16, v46
	v_and_b32_e32 v229, 0xffff0000, v46
	v_pk_fma_f32 v[226:227], v[140:141], v[228:229], v[226:227]
	v_pk_mul_f32 v[224:225], v[224:225], v[226:227]
	v_cvt_pk_bf16_f32 v230, v224, v225
	ds_write_b16 v219, v230 offset:640
	ds_write_b16_d16_hi v219, v230 offset:784
	v_lshlrev_b32_e32 v228, 16, v27
	v_and_b32_e32 v229, 0xffff0000, v27
	v_pk_fma_f32 v[224:225], v[102:103], v[228:229], 0 op_sel_hi:[1,1,0]
	v_lshlrev_b32_e32 v228, 16, v35
	v_and_b32_e32 v229, 0xffff0000, v35
	v_pk_fma_f32 v[224:225], v[118:119], v[228:229], v[224:225]
	v_lshlrev_b32_e32 v228, 16, v43
	v_and_b32_e32 v229, 0xffff0000, v43
	v_pk_fma_f32 v[224:225], v[134:135], v[228:229], v[224:225]
	v_lshlrev_b32_e32 v228, 16, v31
	v_and_b32_e32 v229, 0xffff0000, v31
	v_pk_fma_f32 v[226:227], v[110:111], v[228:229], 0 op_sel_hi:[1,1,0]
	v_lshlrev_b32_e32 v228, 16, v39
	v_and_b32_e32 v229, 0xffff0000, v39
	v_pk_fma_f32 v[226:227], v[126:127], v[228:229], v[226:227]
	v_lshlrev_b32_e32 v228, 16, v47
	v_and_b32_e32 v229, 0xffff0000, v47
	v_pk_fma_f32 v[226:227], v[142:143], v[228:229], v[226:227]
	v_pk_mul_f32 v[224:225], v[224:225], v[226:227]
	v_cvt_pk_bf16_f32 v230, v224, v225
	ds_write_b16 v219, v230 offset:928
	ds_write_b16_d16_hi v219, v230 offset:1072
	s_waitcnt lgkmcnt(0)
	s_barrier
; DI float bflo(unsigned u) { return __uint_as_float(u << 16); }
; DI float bfhi(unsigned u) { return __uint_as_float(u & 0xffff0000u); }
; DI bf16_t f2bf(float x) { return (bf16_t)(pack2(x, 0.f) & 0xffffu); }
; DI void hyena_pre_tile(const Params& p, int item, char* smem) {
;     ...
;     float x1[8], vv[8];
; #pragma unroll
;     for (int j = 0; j < 8; ++j) { x1[j] = 0.f; vv[j] = 0.f; }
; #pragma unroll
;     for (int d = -1; d <= 1; ++d) {
;       int ss = s + d;
;       if (ss >= 0 && ss < 4096) {
;         u32x4 a = ldg16(HY + (size_t)ss * 1536 + 512 + c), bb = ldg16(HY + (size_t)ss * 1536 + 1024 + c);
;         float wa[8], wb[8]; ld8f(p.c_short + (d + 1) * 1536 + 512 + c, wa); ld8f(p.c_short + (d + 1) * 1536 + 1024 + c, wb);
; #pragma unroll
;         for (int q = 0; q < 4; ++q) {
;           x1[2 * q] += wa[2 * q] * bflo(a[q]); x1[2 * q + 1] += wa[2 * q + 1] * bfhi(a[q]);
;           vv[2 * q] += wb[2 * q] * bflo(bb[q]); vv[2 * q + 1] += wb[2 * q + 1] * bfhi(bb[q]);
;         }
;       }
;     }
; #pragma unroll
;     for (int j = 0; j < 8; ++j) sT[(ck * 8 + j) * 72 + row] = f2bf(x1[j] * vv[j]);
;   }
;   __syncthreads();
;   bf16_t* uT = (bf16_t*)(p.hbuf + HB_UT);
; #pragma unroll
;   for (int i = 0; i < 2; ++i) {
;     int row = (tid >> 3) + 32 * i, ck = tid & 7;
;     *(u32x4*)(uT + ((size_t)(ct * 64 + row) * 8 + b) * 4096 + st * 64 + ck * 8) = *(const u32x4*)(sT + row * 72 + ck * 8);
;   }
	ds_read_b128 v[232:235], v220
	ds_read_b128 v[236:239], v220 offset:4608
	s_waitcnt lgkmcnt(1)
	global_store_dwordx4 v[198:199], v[232:235], off
	s_waitcnt lgkmcnt(0)
	global_store_dwordx4 v[210:211], v[236:239], off
	v_lshl_add_u64 v[198:199], v[198:199], 0, s[50:51]
	v_lshl_add_u64 v[210:211], v[210:211], 0, s[50:51]
	global_load_dwordx4 v[0:3], v[192:193], off offset:-4096
	global_load_dwordx4 v[4:7], v[192:193], off offset:-3072
	global_load_dwordx4 v[8:11], v[192:193], off offset:-1024
	global_load_dwordx4 v[12:15], v[192:193], off offset:0
	global_load_dwordx4 v[16:19], v[192:193], off offset:2048
	global_load_dwordx4 v[20:23], v[192:193], off offset:3072
	global_load_dwordx4 v[24:27], v[194:195], off offset:-4096
	global_load_dwordx4 v[28:31], v[194:195], off offset:-3072
	global_load_dwordx4 v[32:35], v[194:195], off offset:-1024
	global_load_dwordx4 v[36:39], v[194:195], off offset:0
	global_load_dwordx4 v[40:43], v[194:195], off offset:2048
	global_load_dwordx4 v[44:47], v[194:195], off offset:3072
	v_lshl_add_u64 v[192:193], v[192:193], 0, s[48:49]
	v_lshl_add_u64 v[194:195], v[194:195], 0, s[48:49]
	s_waitcnt vmcnt(14)
	v_cndmask_b32_e64 v48, 0, v48, s[44:45]
	v_cndmask_b32_e64 v49, 0, v49, s[44:45]
	v_cndmask_b32_e64 v50, 0, v50, s[44:45]
	v_cndmask_b32_e64 v51, 0, v51, s[44:45]
	v_cndmask_b32_e64 v52, 0, v52, s[44:45]
	v_cndmask_b32_e64 v53, 0, v53, s[44:45]
	v_cndmask_b32_e64 v54, 0, v54, s[44:45]
	v_cndmask_b32_e64 v55, 0, v55, s[44:45]
	v_lshlrev_b32_e32 v228, 16, v48
	v_and_b32_e32 v229, 0xffff0000, v48
	v_pk_fma_f32 v[224:225], v[96:97], v[228:229], 0 op_sel_hi:[1,1,0]
	v_lshlrev_b32_e32 v228, 16, v56
	v_and_b32_e32 v229, 0xffff0000, v56
	v_pk_fma_f32 v[224:225], v[112:113], v[228:229], v[224:225]
	v_lshlrev_b32_e32 v228, 16, v64
	v_and_b32_e32 v229, 0xffff0000, v64
	v_pk_fma_f32 v[224:225], v[128:129], v[228:229], v[224:225]
	v_lshlrev_b32_e32 v228, 16, v52
	v_and_b32_e32 v229, 0xffff0000, v52
	v_pk_fma_f32 v[226:227], v[104:105], v[228:229], 0 op_sel_hi:[1,1,0]
	v_lshlrev_b32_e32 v228, 16, v60
	v_and_b32_e32 v229, 0xffff0000, v60
	v_pk_fma_f32 v[226:227], v[120:121], v[228:229], v[226:227]
	v_lshlrev_b32_e32 v228, 16, v68
	v_and_b32_e32 v229, 0xffff0000, v68
	v_pk_fma_f32 v[226:227], v[136:137], v[228:229], v[226:227]
	v_pk_mul_f32 v[224:225], v[224:225], v[226:227]
	v_cvt_pk_bf16_f32 v230, v224, v225
	ds_write_b16 v219, v230 offset:9216
	ds_write_b16_d16_hi v219, v230 offset:9360
	v_lshlrev_b32_e32 v228, 16, v49
	v_and_b32_e32 v229, 0xffff0000, v49
	v_pk_fma_f32 v[224:225], v[98:99], v[228:229], 0 op_sel_hi:[1,1,0]
	v_lshlrev_b32_e32 v228, 16, v57
	v_and_b32_e32 v229, 0xffff0000, v57
	v_pk_fma_f32 v[224:225], v[114:115], v[228:229], v[224:225]
	v_lshlrev_b32_e32 v228, 16, v65
	v_and_b32_e32 v229, 0xffff0000, v65
	v_pk_fma_f32 v[224:225], v[130:131], v[228:229], v[224:225]
	v_lshlrev_b32_e32 v228, 16, v53
	v_and_b32_e32 v229, 0xffff0000, v53
	v_pk_fma_f32 v[226:227], v[106:107], v[228:229], 0 op_sel_hi:[1,1,0]
	v_lshlrev_b32_e32 v228, 16, v61
	v_and_b32_e32 v229, 0xffff0000, v61
	v_pk_fma_f32 v[226:227], v[122:123], v[228:229], v[226:227]
	v_lshlrev_b32_e32 v228, 16, v69
	v_and_b32_e32 v229, 0xffff0000, v69
	v_pk_fma_f32 v[226:227], v[138:139], v[228:229], v[226:227]
	v_pk_mul_f32 v[224:225], v[224:225], v[226:227]
	v_cvt_pk_bf16_f32 v230, v224, v225
	ds_write_b16 v219, v230 offset:9504
	ds_write_b16_d16_hi v219, v230 offset:9648
	v_lshlrev_b32_e32 v228, 16, v50
	v_and_b32_e32 v229, 0xffff0000, v50
	v_pk_fma_f32 v[224:225], v[100:101], v[228:229], 0 op_sel_hi:[1,1,0]
	v_lshlrev_b32_e32 v228, 16, v58
	v_and_b32_e32 v229, 0xffff0000, v58
	v_pk_fma_f32 v[224:225], v[116:117], v[228:229], v[224:225]
	v_lshlrev_b32_e32 v228, 16, v66
	v_and_b32_e32 v229, 0xffff0000, v66
	v_pk_fma_f32 v[224:225], v[132:133], v[228:229], v[224:225]
	v_lshlrev_b32_e32 v228, 16, v54
	v_and_b32_e32 v229, 0xffff0000, v54
	v_pk_fma_f32 v[226:227], v[108:109], v[228:229], 0 op_sel_hi:[1,1,0]
	v_lshlrev_b32_e32 v228, 16, v62
	v_and_b32_e32 v229, 0xffff0000, v62
	v_pk_fma_f32 v[226:227], v[124:125], v[228:229], v[226:227]
	v_lshlrev_b32_e32 v228, 16, v70
	v_and_b32_e32 v229, 0xffff0000, v70
	v_pk_fma_f32 v[226:227], v[140:141], v[228:229], v[226:227]
	v_pk_mul_f32 v[224:225], v[224:225], v[226:227]
	v_cvt_pk_bf16_f32 v230, v224, v225
	ds_write_b16 v219, v230 offset:9792
	ds_write_b16_d16_hi v219, v230 offset:9936
	v_lshlrev_b32_e32 v228, 16, v51
	v_and_b32_e32 v229, 0xffff0000, v51
	v_pk_fma_f32 v[224:225], v[102:103], v[228:229], 0 op_sel_hi:[1,1,0]
	v_lshlrev_b32_e32 v228, 16, v59
	v_and_b32_e32 v229, 0xffff0000, v59
	v_pk_fma_f32 v[224:225], v[118:119], v[228:229], v[224:225]
	v_lshlrev_b32_e32 v228, 16, v67
	v_and_b32_e32 v229, 0xffff0000, v67
	v_pk_fma_f32 v[224:225], v[134:135], v[228:229], v[224:225]
	v_lshlrev_b32_e32 v228, 16, v55
	v_and_b32_e32 v229, 0xffff0000, v55
	v_pk_fma_f32 v[226:227], v[110:111], v[228:229], 0 op_sel_hi:[1,1,0]
	v_lshlrev_b32_e32 v228, 16, v63
	v_and_b32_e32 v229, 0xffff0000, v63
	v_pk_fma_f32 v[226:227], v[126:127], v[228:229], v[226:227]
	v_lshlrev_b32_e32 v228, 16, v71
	v_and_b32_e32 v229, 0xffff0000, v71
	v_pk_fma_f32 v[226:227], v[142:143], v[228:229], v[226:227]
	v_pk_mul_f32 v[224:225], v[224:225], v[226:227]
	v_cvt_pk_bf16_f32 v230, v224, v225
	ds_write_b16 v219, v230 offset:10080
	ds_write_b16_d16_hi v219, v230 offset:10224
	v_cndmask_b32_e64 v88, 0, v88, s[46:47]
	v_cndmask_b32_e64 v89, 0, v89, s[46:47]
	v_cndmask_b32_e64 v90, 0, v90, s[46:47]
	v_cndmask_b32_e64 v91, 0, v91, s[46:47]
	v_cndmask_b32_e64 v92, 0, v92, s[46:47]
	v_cndmask_b32_e64 v93, 0, v93, s[46:47]
	v_cndmask_b32_e64 v94, 0, v94, s[46:47]
; DI float bflo(unsigned u) { return __uint_as_float(u << 16); }
; DI float bfhi(unsigned u) { return __uint_as_float(u & 0xffff0000u); }
; DI bf16_t f2bf(float x) { return (bf16_t)(pack2(x, 0.f) & 0xffffu); }
; DI void hyena_pre_tile(const Params& p, int item, char* smem) {
;     ...
; #pragma unroll
;   for (int i = 0; i < 2; ++i) {
;     int row = (tid >> 3) + 32 * i, ck = tid & 7, s = st * 64 + row, c = ct * 64 + ck * 8;
;     float x1[8], vv[8];
; #pragma unroll
;     for (int j = 0; j < 8; ++j) { x1[j] = 0.f; vv[j] = 0.f; }
; #pragma unroll
;     for (int d = -1; d <= 1; ++d) {
;       int ss = s + d;
;       if (ss >= 0 && ss < 4096) {
;         u32x4 a = ldg16(HY + (size_t)ss * 1536 + 512 + c), bb = ldg16(HY + (size_t)ss * 1536 + 1024 + c);
;         float wa[8], wb[8]; ld8f(p.c_short + (d + 1) * 1536 + 512 + c, wa); ld8f(p.c_short + (d + 1) * 1536 + 1024 + c, wb);
; #pragma unroll
;         for (int q = 0; q < 4; ++q) {
;           x1[2 * q] += wa[2 * q] * bflo(a[q]); x1[2 * q + 1] += wa[2 * q + 1] * bfhi(a[q]);
;           vv[2 * q] += wb[2 * q] * bflo(bb[q]); vv[2 * q + 1] += wb[2 * q + 1] * bfhi(bb[q]);
;         }
;       }
;     }
; #pragma unroll
;     for (int j = 0; j < 8; ++j) sT[(ck * 8 + j) * 72 + row] = f2bf(x1[j] * vv[j]);
;   }
;   __syncthreads();
;   bf16_t* uT = (bf16_t*)(p.hbuf + HB_UT);
; #pragma unroll
;   for (int i = 0; i < 2; ++i) {
;     int row = (tid >> 3) + 32 * i, ck = tid & 7;
;     *(u32x4*)(uT + ((size_t)(ct * 64 + row) * 8 + b) * 4096 + st * 64 + ck * 8) = *(const u32x4*)(sT + row * 72 + ck * 8);
;   }
	v_cndmask_b32_e64 v95, 0, v95, s[46:47]
	v_lshlrev_b32_e32 v228, 16, v72
	v_and_b32_e32 v229, 0xffff0000, v72
	v_pk_fma_f32 v[224:225], v[96:97], v[228:229], 0 op_sel_hi:[1,1,0]
	v_lshlrev_b32_e32 v228, 16, v80
	v_and_b32_e32 v229, 0xffff0000, v80
	v_pk_fma_f32 v[224:225], v[112:113], v[228:229], v[224:225]
	v_lshlrev_b32_e32 v228, 16, v88
	v_and_b32_e32 v229, 0xffff0000, v88
	v_pk_fma_f32 v[224:225], v[128:129], v[228:229], v[224:225]
	v_lshlrev_b32_e32 v228, 16, v76
	v_and_b32_e32 v229, 0xffff0000, v76
	v_pk_fma_f32 v[226:227], v[104:105], v[228:229], 0 op_sel_hi:[1,1,0]
	v_lshlrev_b32_e32 v228, 16, v84
	v_and_b32_e32 v229, 0xffff0000, v84
	v_pk_fma_f32 v[226:227], v[120:121], v[228:229], v[226:227]
	v_lshlrev_b32_e32 v228, 16, v92
	v_and_b32_e32 v229, 0xffff0000, v92
	v_pk_fma_f32 v[226:227], v[136:137], v[228:229], v[226:227]
	v_pk_mul_f32 v[224:225], v[224:225], v[226:227]
	v_cvt_pk_bf16_f32 v230, v224, v225
	ds_write_b16 v219, v230 offset:9280
	ds_write_b16_d16_hi v219, v230 offset:9424
	v_lshlrev_b32_e32 v228, 16, v73
	v_and_b32_e32 v229, 0xffff0000, v73
	v_pk_fma_f32 v[224:225], v[98:99], v[228:229], 0 op_sel_hi:[1,1,0]
	v_lshlrev_b32_e32 v228, 16, v81
	v_and_b32_e32 v229, 0xffff0000, v81
	v_pk_fma_f32 v[224:225], v[114:115], v[228:229], v[224:225]
	v_lshlrev_b32_e32 v228, 16, v89
	v_and_b32_e32 v229, 0xffff0000, v89
	v_pk_fma_f32 v[224:225], v[130:131], v[228:229], v[224:225]
	v_lshlrev_b32_e32 v228, 16, v77
	v_and_b32_e32 v229, 0xffff0000, v77
	v_pk_fma_f32 v[226:227], v[106:107], v[228:229], 0 op_sel_hi:[1,1,0]
	v_lshlrev_b32_e32 v228, 16, v85
	v_and_b32_e32 v229, 0xffff0000, v85
	v_pk_fma_f32 v[226:227], v[122:123], v[228:229], v[226:227]
	v_lshlrev_b32_e32 v228, 16, v93
	v_and_b32_e32 v229, 0xffff0000, v93
	v_pk_fma_f32 v[226:227], v[138:139], v[228:229], v[226:227]
	v_pk_mul_f32 v[224:225], v[224:225], v[226:227]
	v_cvt_pk_bf16_f32 v230, v224, v225
	ds_write_b16 v219, v230 offset:9568
	ds_write_b16_d16_hi v219, v230 offset:9712
	v_lshlrev_b32_e32 v228, 16, v74
	v_and_b32_e32 v229, 0xffff0000, v74
	v_pk_fma_f32 v[224:225], v[100:101], v[228:229], 0 op_sel_hi:[1,1,0]
	v_lshlrev_b32_e32 v228, 16, v82
	v_and_b32_e32 v229, 0xffff0000, v82
	v_pk_fma_f32 v[224:225], v[116:117], v[228:229], v[224:225]
	v_lshlrev_b32_e32 v228, 16, v90
	v_and_b32_e32 v229, 0xffff0000, v90
	v_pk_fma_f32 v[224:225], v[132:133], v[228:229], v[224:225]
	v_lshlrev_b32_e32 v228, 16, v78
	v_and_b32_e32 v229, 0xffff0000, v78
	v_pk_fma_f32 v[226:227], v[108:109], v[228:229], 0 op_sel_hi:[1,1,0]
	v_lshlrev_b32_e32 v228, 16, v86
	v_and_b32_e32 v229, 0xffff0000, v86
	v_pk_fma_f32 v[226:227], v[124:125], v[228:229], v[226:227]
	v_lshlrev_b32_e32 v228, 16, v94
	v_and_b32_e32 v229, 0xffff0000, v94
	v_pk_fma_f32 v[226:227], v[140:141], v[228:229], v[226:227]
	v_pk_mul_f32 v[224:225], v[224:225], v[226:227]
	v_cvt_pk_bf16_f32 v230, v224, v225
	ds_write_b16 v219, v230 offset:9856
	ds_write_b16_d16_hi v219, v230 offset:10000
	v_lshlrev_b32_e32 v228, 16, v75
	v_and_b32_e32 v229, 0xffff0000, v75
	v_pk_fma_f32 v[224:225], v[102:103], v[228:229], 0 op_sel_hi:[1,1,0]
	v_lshlrev_b32_e32 v228, 16, v83
	v_and_b32_e32 v229, 0xffff0000, v83
	v_pk_fma_f32 v[224:225], v[118:119], v[228:229], v[224:225]
	v_lshlrev_b32_e32 v228, 16, v91
	v_and_b32_e32 v229, 0xffff0000, v91
	v_pk_fma_f32 v[224:225], v[134:135], v[228:229], v[224:225]
	v_lshlrev_b32_e32 v228, 16, v79
	v_and_b32_e32 v229, 0xffff0000, v79
	v_pk_fma_f32 v[226:227], v[110:111], v[228:229], 0 op_sel_hi:[1,1,0]
	v_lshlrev_b32_e32 v228, 16, v87
	v_and_b32_e32 v229, 0xffff0000, v87
	v_pk_fma_f32 v[226:227], v[126:127], v[228:229], v[226:227]
	v_lshlrev_b32_e32 v228, 16, v95
	v_and_b32_e32 v229, 0xffff0000, v95
	v_pk_fma_f32 v[226:227], v[142:143], v[228:229], v[226:227]
	v_pk_mul_f32 v[224:225], v[224:225], v[226:227]
	v_cvt_pk_bf16_f32 v230, v224, v225
	ds_write_b16 v219, v230 offset:10144
	ds_write_b16_d16_hi v219, v230 offset:10288
	s_waitcnt lgkmcnt(0)
	s_barrier
	ds_read_b128 v[232:235], v220 offset:9216
	ds_read_b128 v[236:239], v220 offset:13824
	s_waitcnt lgkmcnt(1)
	global_store_dwordx4 v[198:199], v[232:235], off
	s_waitcnt lgkmcnt(0)
	global_store_dwordx4 v[210:211], v[236:239], off
	v_lshl_add_u64 v[198:199], v[198:199], 0, s[50:51]
	v_lshl_add_u64 v[210:211], v[210:211], 0, s[50:51]
	global_load_dwordx4 v[48:51], v[192:193], off offset:-4096
	global_load_dwordx4 v[52:55], v[192:193], off offset:-3072
	global_load_dwordx4 v[56:59], v[192:193], off offset:-1024
	global_load_dwordx4 v[60:63], v[192:193], off offset:0
	global_load_dwordx4 v[64:67], v[192:193], off offset:2048
	global_load_dwordx4 v[68:71], v[192:193], off offset:3072
	global_load_dwordx4 v[72:75], v[194:195], off offset:-4096
	global_load_dwordx4 v[76:79], v[194:195], off offset:-3072
	global_load_dwordx4 v[80:83], v[194:195], off offset:-1024
	global_load_dwordx4 v[84:87], v[194:195], off offset:0
	global_load_dwordx4 v[88:91], v[194:195], off offset:2048
	global_load_dwordx4 v[92:95], v[194:195], off offset:3072
	v_lshl_add_u64 v[192:193], v[192:193], 0, s[48:49]
	v_lshl_add_u64 v[194:195], v[194:195], 0, s[48:49]
	s_waitcnt vmcnt(14)
; DI float bflo(unsigned u) { return __uint_as_float(u << 16); }
; DI float bfhi(unsigned u) { return __uint_as_float(u & 0xffff0000u); }
; DI bf16_t f2bf(float x) { return (bf16_t)(pack2(x, 0.f) & 0xffffu); }
; DI void hyena_pre_tile(const Params& p, int item, char* smem) {
;     ...
; #pragma unroll
;   for (int i = 0; i < 2; ++i) {
;     int row = (tid >> 3) + 32 * i, ck = tid & 7, s = st * 64 + row, c = ct * 64 + ck * 8;
;     float x1[8], vv[8];
; #pragma unroll
;     for (int j = 0; j < 8; ++j) { x1[j] = 0.f; vv[j] = 0.f; }
; #pragma unroll
;     for (int d = -1; d <= 1; ++d) {
;       int ss = s + d;
;       if (ss >= 0 && ss < 4096) {
;         u32x4 a = ldg16(HY + (size_t)ss * 1536 + 512 + c), bb = ldg16(HY + (size_t)ss * 1536 + 1024 + c);
;         float wa[8], wb[8]; ld8f(p.c_short + (d + 1) * 1536 + 512 + c, wa); ld8f(p.c_short + (d + 1) * 1536 + 1024 + c, wb);
; #pragma unroll
;         for (int q = 0; q < 4; ++q) {
;           x1[2 * q] += wa[2 * q] * bflo(a[q]); x1[2 * q + 1] += wa[2 * q + 1] * bfhi(a[q]);
;           vv[2 * q] += wb[2 * q] * bflo(bb[q]); vv[2 * q + 1] += wb[2 * q + 1] * bfhi(bb[q]);
;         }
;       }
;     }
; #pragma unroll
;     for (int j = 0; j < 8; ++j) sT[(ck * 8 + j) * 72 + row] = f2bf(x1[j] * vv[j]);
;   }
	v_cndmask_b32_e64 v0, 0, v0, s[44:45]
	v_cndmask_b32_e64 v1, 0, v1, s[44:45]
	v_cndmask_b32_e64 v2, 0, v2, s[44:45]
	v_cndmask_b32_e64 v3, 0, v3, s[44:45]
	v_cndmask_b32_e64 v4, 0, v4, s[44:45]
	v_cndmask_b32_e64 v5, 0, v5, s[44:45]
	v_cndmask_b32_e64 v6, 0, v6, s[44:45]
	v_cndmask_b32_e64 v7, 0, v7, s[44:45]
	v_lshlrev_b32_e32 v228, 16, v0
	v_and_b32_e32 v229, 0xffff0000, v0
	v_pk_fma_f32 v[224:225], v[96:97], v[228:229], 0 op_sel_hi:[1,1,0]
	v_lshlrev_b32_e32 v228, 16, v8
	v_and_b32_e32 v229, 0xffff0000, v8
	v_pk_fma_f32 v[224:225], v[112:113], v[228:229], v[224:225]
	v_lshlrev_b32_e32 v228, 16, v16
	v_and_b32_e32 v229, 0xffff0000, v16
	v_pk_fma_f32 v[224:225], v[128:129], v[228:229], v[224:225]
	v_lshlrev_b32_e32 v228, 16, v4
	v_and_b32_e32 v229, 0xffff0000, v4
	v_pk_fma_f32 v[226:227], v[104:105], v[228:229], 0 op_sel_hi:[1,1,0]
	v_lshlrev_b32_e32 v228, 16, v12
	v_and_b32_e32 v229, 0xffff0000, v12
	v_pk_fma_f32 v[226:227], v[120:121], v[228:229], v[226:227]
	v_lshlrev_b32_e32 v228, 16, v20
	v_and_b32_e32 v229, 0xffff0000, v20
	v_pk_fma_f32 v[226:227], v[136:137], v[228:229], v[226:227]
	v_pk_mul_f32 v[224:225], v[224:225], v[226:227]
	v_cvt_pk_bf16_f32 v230, v224, v225
	ds_write_b16 v219, v230
	ds_write_b16_d16_hi v219, v230 offset:144
	v_lshlrev_b32_e32 v228, 16, v1
	v_and_b32_e32 v229, 0xffff0000, v1
	v_pk_fma_f32 v[224:225], v[98:99], v[228:229], 0 op_sel_hi:[1,1,0]
	v_lshlrev_b32_e32 v228, 16, v9
	v_and_b32_e32 v229, 0xffff0000, v9
	v_pk_fma_f32 v[224:225], v[114:115], v[228:229], v[224:225]
	v_lshlrev_b32_e32 v228, 16, v17
	v_and_b32_e32 v229, 0xffff0000, v17
	v_pk_fma_f32 v[224:225], v[130:131], v[228:229], v[224:225]
	v_lshlrev_b32_e32 v228, 16, v5
	v_and_b32_e32 v229, 0xffff0000, v5
	v_pk_fma_f32 v[226:227], v[106:107], v[228:229], 0 op_sel_hi:[1,1,0]
	v_lshlrev_b32_e32 v228, 16, v13
	v_and_b32_e32 v229, 0xffff0000, v13
	v_pk_fma_f32 v[226:227], v[122:123], v[228:229], v[226:227]
	v_lshlrev_b32_e32 v228, 16, v21
	v_and_b32_e32 v229, 0xffff0000, v21
	v_pk_fma_f32 v[226:227], v[138:139], v[228:229], v[226:227]
	v_pk_mul_f32 v[224:225], v[224:225], v[226:227]
	v_cvt_pk_bf16_f32 v230, v224, v225
	ds_write_b16 v219, v230 offset:288
	ds_write_b16_d16_hi v219, v230 offset:432
	v_lshlrev_b32_e32 v228, 16, v2
	v_and_b32_e32 v229, 0xffff0000, v2
	v_pk_fma_f32 v[224:225], v[100:101], v[228:229], 0 op_sel_hi:[1,1,0]
	v_lshlrev_b32_e32 v228, 16, v10
	v_and_b32_e32 v229, 0xffff0000, v10
	v_pk_fma_f32 v[224:225], v[116:117], v[228:229], v[224:225]
	v_lshlrev_b32_e32 v228, 16, v18
	v_and_b32_e32 v229, 0xffff0000, v18
	v_pk_fma_f32 v[224:225], v[132:133], v[228:229], v[224:225]
	v_lshlrev_b32_e32 v228, 16, v6
	v_and_b32_e32 v229, 0xffff0000, v6
	v_pk_fma_f32 v[226:227], v[108:109], v[228:229], 0 op_sel_hi:[1,1,0]
	v_lshlrev_b32_e32 v228, 16, v14
	v_and_b32_e32 v229, 0xffff0000, v14
	v_pk_fma_f32 v[226:227], v[124:125], v[228:229], v[226:227]
	v_lshlrev_b32_e32 v228, 16, v22
	v_and_b32_e32 v229, 0xffff0000, v22
	v_pk_fma_f32 v[226:227], v[140:141], v[228:229], v[226:227]
	v_pk_mul_f32 v[224:225], v[224:225], v[226:227]
	v_cvt_pk_bf16_f32 v230, v224, v225
	ds_write_b16 v219, v230 offset:576
	ds_write_b16_d16_hi v219, v230 offset:720
	v_lshlrev_b32_e32 v228, 16, v3
	v_and_b32_e32 v229, 0xffff0000, v3
	v_pk_fma_f32 v[224:225], v[102:103], v[228:229], 0 op_sel_hi:[1,1,0]
	v_lshlrev_b32_e32 v228, 16, v11
	v_and_b32_e32 v229, 0xffff0000, v11
	v_pk_fma_f32 v[224:225], v[118:119], v[228:229], v[224:225]
	v_lshlrev_b32_e32 v228, 16, v19
	v_and_b32_e32 v229, 0xffff0000, v19
	v_pk_fma_f32 v[224:225], v[134:135], v[228:229], v[224:225]
	v_lshlrev_b32_e32 v228, 16, v7
	v_and_b32_e32 v229, 0xffff0000, v7
	v_pk_fma_f32 v[226:227], v[110:111], v[228:229], 0 op_sel_hi:[1,1,0]
	v_lshlrev_b32_e32 v228, 16, v15
	v_and_b32_e32 v229, 0xffff0000, v15
	v_pk_fma_f32 v[226:227], v[126:127], v[228:229], v[226:227]
	v_lshlrev_b32_e32 v228, 16, v23
	v_and_b32_e32 v229, 0xffff0000, v23
	v_pk_fma_f32 v[226:227], v[142:143], v[228:229], v[226:227]
	v_pk_mul_f32 v[224:225], v[224:225], v[226:227]
	v_cvt_pk_bf16_f32 v230, v224, v225
	ds_write_b16 v219, v230 offset:864
	ds_write_b16_d16_hi v219, v230 offset:1008
	v_cndmask_b32_e64 v40, 0, v40, s[46:47]
	v_cndmask_b32_e64 v41, 0, v41, s[46:47]
	v_cndmask_b32_e64 v42, 0, v42, s[46:47]
	v_cndmask_b32_e64 v43, 0, v43, s[46:47]
	v_cndmask_b32_e64 v44, 0, v44, s[46:47]
	v_cndmask_b32_e64 v45, 0, v45, s[46:47]
	v_cndmask_b32_e64 v46, 0, v46, s[46:47]
	v_cndmask_b32_e64 v47, 0, v47, s[46:47]
	v_lshlrev_b32_e32 v228, 16, v24
	v_and_b32_e32 v229, 0xffff0000, v24
	v_pk_fma_f32 v[224:225], v[96:97], v[228:229], 0 op_sel_hi:[1,1,0]
	v_lshlrev_b32_e32 v228, 16, v32
	v_and_b32_e32 v229, 0xffff0000, v32
	v_pk_fma_f32 v[224:225], v[112:113], v[228:229], v[224:225]
	v_lshlrev_b32_e32 v228, 16, v40
	v_and_b32_e32 v229, 0xffff0000, v40
	v_pk_fma_f32 v[224:225], v[128:129], v[228:229], v[224:225]
	v_lshlrev_b32_e32 v228, 16, v28
	v_and_b32_e32 v229, 0xffff0000, v28
	v_pk_fma_f32 v[226:227], v[104:105], v[228:229], 0 op_sel_hi:[1,1,0]
	v_lshlrev_b32_e32 v228, 16, v36
	v_and_b32_e32 v229, 0xffff0000, v36
	v_pk_fma_f32 v[226:227], v[120:121], v[228:229], v[226:227]
	v_lshlrev_b32_e32 v228, 16, v44
	v_and_b32_e32 v229, 0xffff0000, v44
	v_pk_fma_f32 v[226:227], v[136:137], v[228:229], v[226:227]
	v_pk_mul_f32 v[224:225], v[224:225], v[226:227]
	v_cvt_pk_bf16_f32 v230, v224, v225
	ds_write_b16 v219, v230 offset:64
	ds_write_b16_d16_hi v219, v230 offset:208
	v_lshlrev_b32_e32 v228, 16, v25
	v_and_b32_e32 v229, 0xffff0000, v25
	v_pk_fma_f32 v[224:225], v[98:99], v[228:229], 0 op_sel_hi:[1,1,0]
	v_lshlrev_b32_e32 v228, 16, v33
	v_and_b32_e32 v229, 0xffff0000, v33
; DI float bflo(unsigned u) { return __uint_as_float(u << 16); }
; DI float bfhi(unsigned u) { return __uint_as_float(u & 0xffff0000u); }
; DI bf16_t f2bf(float x) { return (bf16_t)(pack2(x, 0.f) & 0xffffu); }
; DI void hyena_pre_tile(const Params& p, int item, char* smem) {
;     ...
; #pragma unroll
;   for (int i = 0; i < 2; ++i) {
;     int row = (tid >> 3) + 32 * i, ck = tid & 7, s = st * 64 + row, c = ct * 64 + ck * 8;
;     float x1[8], vv[8];
; #pragma unroll
;     for (int j = 0; j < 8; ++j) { x1[j] = 0.f; vv[j] = 0.f; }
; #pragma unroll
;     for (int d = -1; d <= 1; ++d) {
;       int ss = s + d;
;       if (ss >= 0 && ss < 4096) {
;         u32x4 a = ldg16(HY + (size_t)ss * 1536 + 512 + c), bb = ldg16(HY + (size_t)ss * 1536 + 1024 + c);
;         float wa[8], wb[8]; ld8f(p.c_short + (d + 1) * 1536 + 512 + c, wa); ld8f(p.c_short + (d + 1) * 1536 + 1024 + c, wb);
; #pragma unroll
;         for (int q = 0; q < 4; ++q) {
;           x1[2 * q] += wa[2 * q] * bflo(a[q]); x1[2 * q + 1] += wa[2 * q + 1] * bfhi(a[q]);
;           vv[2 * q] += wb[2 * q] * bflo(bb[q]); vv[2 * q + 1] += wb[2 * q + 1] * bfhi(bb[q]);
;         }
;       }
;     }
; #pragma unroll
;     for (int j = 0; j < 8; ++j) sT[(ck * 8 + j) * 72 + row] = f2bf(x1[j] * vv[j]);
;   }
;   __syncthreads();
;   bf16_t* uT = (bf16_t*)(p.hbuf + HB_UT);
; #pragma unroll
;   for (int i = 0; i < 2; ++i) {
;     int row = (tid >> 3) + 32 * i, ck = tid & 7;
;     *(u32x4*)(uT + ((size_t)(ct * 64 + row) * 8 + b) * 4096 + st * 64 + ck * 8) = *(const u32x4*)(sT + row * 72 + ck * 8);
;   }
	v_pk_fma_f32 v[224:225], v[114:115], v[228:229], v[224:225]
	v_lshlrev_b32_e32 v228, 16, v41
	v_and_b32_e32 v229, 0xffff0000, v41
	v_pk_fma_f32 v[224:225], v[130:131], v[228:229], v[224:225]
	v_lshlrev_b32_e32 v228, 16, v29
	v_and_b32_e32 v229, 0xffff0000, v29
	v_pk_fma_f32 v[226:227], v[106:107], v[228:229], 0 op_sel_hi:[1,1,0]
	v_lshlrev_b32_e32 v228, 16, v37
	v_and_b32_e32 v229, 0xffff0000, v37
	v_pk_fma_f32 v[226:227], v[122:123], v[228:229], v[226:227]
	v_lshlrev_b32_e32 v228, 16, v45
	v_and_b32_e32 v229, 0xffff0000, v45
	v_pk_fma_f32 v[226:227], v[138:139], v[228:229], v[226:227]
	v_pk_mul_f32 v[224:225], v[224:225], v[226:227]
	v_cvt_pk_bf16_f32 v230, v224, v225
	ds_write_b16 v219, v230 offset:352
	ds_write_b16_d16_hi v219, v230 offset:496
	v_lshlrev_b32_e32 v228, 16, v26
	v_and_b32_e32 v229, 0xffff0000, v26
	v_pk_fma_f32 v[224:225], v[100:101], v[228:229], 0 op_sel_hi:[1,1,0]
	v_lshlrev_b32_e32 v228, 16, v34
	v_and_b32_e32 v229, 0xffff0000, v34
	v_pk_fma_f32 v[224:225], v[116:117], v[228:229], v[224:225]
	v_lshlrev_b32_e32 v228, 16, v42
	v_and_b32_e32 v229, 0xffff0000, v42
	v_pk_fma_f32 v[224:225], v[132:133], v[228:229], v[224:225]
	v_lshlrev_b32_e32 v228, 16, v30
	v_and_b32_e32 v229, 0xffff0000, v30
	v_pk_fma_f32 v[226:227], v[108:109], v[228:229], 0 op_sel_hi:[1,1,0]
	v_lshlrev_b32_e32 v228, 16, v38
	v_and_b32_e32 v229, 0xffff0000, v38
	v_pk_fma_f32 v[226:227], v[124:125], v[228:229], v[226:227]
	v_lshlrev_b32_e32 v228, 16, v46
	v_and_b32_e32 v229, 0xffff0000, v46
	v_pk_fma_f32 v[226:227], v[140:141], v[228:229], v[226:227]
	v_pk_mul_f32 v[224:225], v[224:225], v[226:227]
	v_cvt_pk_bf16_f32 v230, v224, v225
	ds_write_b16 v219, v230 offset:640
	ds_write_b16_d16_hi v219, v230 offset:784
	v_lshlrev_b32_e32 v228, 16, v27
	v_and_b32_e32 v229, 0xffff0000, v27
	v_pk_fma_f32 v[224:225], v[102:103], v[228:229], 0 op_sel_hi:[1,1,0]
	v_lshlrev_b32_e32 v228, 16, v35
	v_and_b32_e32 v229, 0xffff0000, v35
	v_pk_fma_f32 v[224:225], v[118:119], v[228:229], v[224:225]
	v_lshlrev_b32_e32 v228, 16, v43
	v_and_b32_e32 v229, 0xffff0000, v43
	v_pk_fma_f32 v[224:225], v[134:135], v[228:229], v[224:225]
	v_lshlrev_b32_e32 v228, 16, v31
	v_and_b32_e32 v229, 0xffff0000, v31
	v_pk_fma_f32 v[226:227], v[110:111], v[228:229], 0 op_sel_hi:[1,1,0]
	v_lshlrev_b32_e32 v228, 16, v39
	v_and_b32_e32 v229, 0xffff0000, v39
	v_pk_fma_f32 v[226:227], v[126:127], v[228:229], v[226:227]
	v_lshlrev_b32_e32 v228, 16, v47
	v_and_b32_e32 v229, 0xffff0000, v47
	v_pk_fma_f32 v[226:227], v[142:143], v[228:229], v[226:227]
	v_pk_mul_f32 v[224:225], v[224:225], v[226:227]
	v_cvt_pk_bf16_f32 v230, v224, v225
	ds_write_b16 v219, v230 offset:928
	ds_write_b16_d16_hi v219, v230 offset:1072
	s_waitcnt lgkmcnt(0)
	s_barrier
	ds_read_b128 v[232:235], v220
	ds_read_b128 v[236:239], v220 offset:4608
	s_waitcnt lgkmcnt(1)
	global_store_dwordx4 v[198:199], v[232:235], off
	s_waitcnt lgkmcnt(0)
	global_store_dwordx4 v[210:211], v[236:239], off
	v_lshl_add_u64 v[198:199], v[198:199], 0, s[50:51]
	v_lshl_add_u64 v[210:211], v[210:211], 0, s[50:51]
	s_waitcnt vmcnt(2)
	v_cndmask_b32_e64 v48, 0, v48, s[44:45]
	v_cndmask_b32_e64 v49, 0, v49, s[44:45]
	v_cndmask_b32_e64 v50, 0, v50, s[44:45]
	v_cndmask_b32_e64 v51, 0, v51, s[44:45]
	v_cndmask_b32_e64 v52, 0, v52, s[44:45]
	v_cndmask_b32_e64 v53, 0, v53, s[44:45]
	v_cndmask_b32_e64 v54, 0, v54, s[44:45]
	v_cndmask_b32_e64 v55, 0, v55, s[44:45]
	v_lshlrev_b32_e32 v228, 16, v48
	v_and_b32_e32 v229, 0xffff0000, v48
	v_pk_fma_f32 v[224:225], v[96:97], v[228:229], 0 op_sel_hi:[1,1,0]
	v_lshlrev_b32_e32 v228, 16, v56
	v_and_b32_e32 v229, 0xffff0000, v56
	v_pk_fma_f32 v[224:225], v[112:113], v[228:229], v[224:225]
	v_lshlrev_b32_e32 v228, 16, v64
	v_and_b32_e32 v229, 0xffff0000, v64
	v_pk_fma_f32 v[224:225], v[128:129], v[228:229], v[224:225]
	v_lshlrev_b32_e32 v228, 16, v52
	v_and_b32_e32 v229, 0xffff0000, v52
	v_pk_fma_f32 v[226:227], v[104:105], v[228:229], 0 op_sel_hi:[1,1,0]
	v_lshlrev_b32_e32 v228, 16, v60
	v_and_b32_e32 v229, 0xffff0000, v60
	v_pk_fma_f32 v[226:227], v[120:121], v[228:229], v[226:227]
	v_lshlrev_b32_e32 v228, 16, v68
	v_and_b32_e32 v229, 0xffff0000, v68
	v_pk_fma_f32 v[226:227], v[136:137], v[228:229], v[226:227]
	v_pk_mul_f32 v[224:225], v[224:225], v[226:227]
	v_cvt_pk_bf16_f32 v230, v224, v225
	ds_write_b16 v219, v230 offset:9216
	ds_write_b16_d16_hi v219, v230 offset:9360
	v_lshlrev_b32_e32 v228, 16, v49
	v_and_b32_e32 v229, 0xffff0000, v49
	v_pk_fma_f32 v[224:225], v[98:99], v[228:229], 0 op_sel_hi:[1,1,0]
	v_lshlrev_b32_e32 v228, 16, v57
	v_and_b32_e32 v229, 0xffff0000, v57
	v_pk_fma_f32 v[224:225], v[114:115], v[228:229], v[224:225]
	v_lshlrev_b32_e32 v228, 16, v65
	v_and_b32_e32 v229, 0xffff0000, v65
	v_pk_fma_f32 v[224:225], v[130:131], v[228:229], v[224:225]
	v_lshlrev_b32_e32 v228, 16, v53
	v_and_b32_e32 v229, 0xffff0000, v53
	v_pk_fma_f32 v[226:227], v[106:107], v[228:229], 0 op_sel_hi:[1,1,0]
	v_lshlrev_b32_e32 v228, 16, v61
	v_and_b32_e32 v229, 0xffff0000, v61
	v_pk_fma_f32 v[226:227], v[122:123], v[228:229], v[226:227]
	v_lshlrev_b32_e32 v228, 16, v69
	v_and_b32_e32 v229, 0xffff0000, v69
	v_pk_fma_f32 v[226:227], v[138:139], v[228:229], v[226:227]
	v_pk_mul_f32 v[224:225], v[224:225], v[226:227]
	v_cvt_pk_bf16_f32 v230, v224, v225
	ds_write_b16 v219, v230 offset:9504
	ds_write_b16_d16_hi v219, v230 offset:9648
	v_lshlrev_b32_e32 v228, 16, v50
	v_and_b32_e32 v229, 0xffff0000, v50
	v_pk_fma_f32 v[224:225], v[100:101], v[228:229], 0 op_sel_hi:[1,1,0]
	v_lshlrev_b32_e32 v228, 16, v58
	v_and_b32_e32 v229, 0xffff0000, v58
	v_pk_fma_f32 v[224:225], v[116:117], v[228:229], v[224:225]
	v_lshlrev_b32_e32 v228, 16, v66
; DI float bflo(unsigned u) { return __uint_as_float(u << 16); }
; DI float bfhi(unsigned u) { return __uint_as_float(u & 0xffff0000u); }
; DI bf16_t f2bf(float x) { return (bf16_t)(pack2(x, 0.f) & 0xffffu); }
; DI void hyena_pre_tile(const Params& p, int item, char* smem) {
;     ...
; #pragma unroll
;   for (int i = 0; i < 2; ++i) {
;     int row = (tid >> 3) + 32 * i, ck = tid & 7, s = st * 64 + row, c = ct * 64 + ck * 8;
;     float x1[8], vv[8];
; #pragma unroll
;     for (int j = 0; j < 8; ++j) { x1[j] = 0.f; vv[j] = 0.f; }
; #pragma unroll
;     for (int d = -1; d <= 1; ++d) {
;       int ss = s + d;
;       if (ss >= 0 && ss < 4096) {
;         u32x4 a = ldg16(HY + (size_t)ss * 1536 + 512 + c), bb = ldg16(HY + (size_t)ss * 1536 + 1024 + c);
;         float wa[8], wb[8]; ld8f(p.c_short + (d + 1) * 1536 + 512 + c, wa); ld8f(p.c_short + (d + 1) * 1536 + 1024 + c, wb);
; #pragma unroll
;         for (int q = 0; q < 4; ++q) {
;           x1[2 * q] += wa[2 * q] * bflo(a[q]); x1[2 * q + 1] += wa[2 * q + 1] * bfhi(a[q]);
;           vv[2 * q] += wb[2 * q] * bflo(bb[q]); vv[2 * q + 1] += wb[2 * q + 1] * bfhi(bb[q]);
;         }
;       }
;     }
; #pragma unroll
;     for (int j = 0; j < 8; ++j) sT[(ck * 8 + j) * 72 + row] = f2bf(x1[j] * vv[j]);
;   }
;   __syncthreads();
;   bf16_t* uT = (bf16_t*)(p.hbuf + HB_UT);
; #pragma unroll
;   for (int i = 0; i < 2; ++i) {
;     int row = (tid >> 3) + 32 * i, ck = tid & 7;
;     *(u32x4*)(uT + ((size_t)(ct * 64 + row) * 8 + b) * 4096 + st * 64 + ck * 8) = *(const u32x4*)(sT + row * 72 + ck * 8);
;   }
	v_and_b32_e32 v229, 0xffff0000, v66
	v_pk_fma_f32 v[224:225], v[132:133], v[228:229], v[224:225]
	v_lshlrev_b32_e32 v228, 16, v54
	v_and_b32_e32 v229, 0xffff0000, v54
	v_pk_fma_f32 v[226:227], v[108:109], v[228:229], 0 op_sel_hi:[1,1,0]
	v_lshlrev_b32_e32 v228, 16, v62
	v_and_b32_e32 v229, 0xffff0000, v62
	v_pk_fma_f32 v[226:227], v[124:125], v[228:229], v[226:227]
	v_lshlrev_b32_e32 v228, 16, v70
	v_and_b32_e32 v229, 0xffff0000, v70
	v_pk_fma_f32 v[226:227], v[140:141], v[228:229], v[226:227]
	v_pk_mul_f32 v[224:225], v[224:225], v[226:227]
	v_cvt_pk_bf16_f32 v230, v224, v225
	ds_write_b16 v219, v230 offset:9792
	ds_write_b16_d16_hi v219, v230 offset:9936
	v_lshlrev_b32_e32 v228, 16, v51
	v_and_b32_e32 v229, 0xffff0000, v51
	v_pk_fma_f32 v[224:225], v[102:103], v[228:229], 0 op_sel_hi:[1,1,0]
	v_lshlrev_b32_e32 v228, 16, v59
	v_and_b32_e32 v229, 0xffff0000, v59
	v_pk_fma_f32 v[224:225], v[118:119], v[228:229], v[224:225]
	v_lshlrev_b32_e32 v228, 16, v67
	v_and_b32_e32 v229, 0xffff0000, v67
	v_pk_fma_f32 v[224:225], v[134:135], v[228:229], v[224:225]
	v_lshlrev_b32_e32 v228, 16, v55
	v_and_b32_e32 v229, 0xffff0000, v55
	v_pk_fma_f32 v[226:227], v[110:111], v[228:229], 0 op_sel_hi:[1,1,0]
	v_lshlrev_b32_e32 v228, 16, v63
	v_and_b32_e32 v229, 0xffff0000, v63
	v_pk_fma_f32 v[226:227], v[126:127], v[228:229], v[226:227]
	v_lshlrev_b32_e32 v228, 16, v71
	v_and_b32_e32 v229, 0xffff0000, v71
	v_pk_fma_f32 v[226:227], v[142:143], v[228:229], v[226:227]
	v_pk_mul_f32 v[224:225], v[224:225], v[226:227]
	v_cvt_pk_bf16_f32 v230, v224, v225
	ds_write_b16 v219, v230 offset:10080
	ds_write_b16_d16_hi v219, v230 offset:10224
	v_cndmask_b32_e64 v88, 0, v88, s[46:47]
	v_cndmask_b32_e64 v89, 0, v89, s[46:47]
	v_cndmask_b32_e64 v90, 0, v90, s[46:47]
	v_cndmask_b32_e64 v91, 0, v91, s[46:47]
	v_cndmask_b32_e64 v92, 0, v92, s[46:47]
	v_cndmask_b32_e64 v93, 0, v93, s[46:47]
	v_cndmask_b32_e64 v94, 0, v94, s[46:47]
	v_cndmask_b32_e64 v95, 0, v95, s[46:47]
	v_lshlrev_b32_e32 v228, 16, v72
	v_and_b32_e32 v229, 0xffff0000, v72
	v_pk_fma_f32 v[224:225], v[96:97], v[228:229], 0 op_sel_hi:[1,1,0]
	v_lshlrev_b32_e32 v228, 16, v80
	v_and_b32_e32 v229, 0xffff0000, v80
	v_pk_fma_f32 v[224:225], v[112:113], v[228:229], v[224:225]
	v_lshlrev_b32_e32 v228, 16, v88
	v_and_b32_e32 v229, 0xffff0000, v88
	v_pk_fma_f32 v[224:225], v[128:129], v[228:229], v[224:225]
	v_lshlrev_b32_e32 v228, 16, v76
	v_and_b32_e32 v229, 0xffff0000, v76
	v_pk_fma_f32 v[226:227], v[104:105], v[228:229], 0 op_sel_hi:[1,1,0]
	v_lshlrev_b32_e32 v228, 16, v84
	v_and_b32_e32 v229, 0xffff0000, v84
	v_pk_fma_f32 v[226:227], v[120:121], v[228:229], v[226:227]
	v_lshlrev_b32_e32 v228, 16, v92
	v_and_b32_e32 v229, 0xffff0000, v92
	v_pk_fma_f32 v[226:227], v[136:137], v[228:229], v[226:227]
	v_pk_mul_f32 v[224:225], v[224:225], v[226:227]
	v_cvt_pk_bf16_f32 v230, v224, v225
	ds_write_b16 v219, v230 offset:9280
	ds_write_b16_d16_hi v219, v230 offset:9424
	v_lshlrev_b32_e32 v228, 16, v73
	v_and_b32_e32 v229, 0xffff0000, v73
	v_pk_fma_f32 v[224:225], v[98:99], v[228:229], 0 op_sel_hi:[1,1,0]
	v_lshlrev_b32_e32 v228, 16, v81
	v_and_b32_e32 v229, 0xffff0000, v81
	v_pk_fma_f32 v[224:225], v[114:115], v[228:229], v[224:225]
	v_lshlrev_b32_e32 v228, 16, v89
	v_and_b32_e32 v229, 0xffff0000, v89
	v_pk_fma_f32 v[224:225], v[130:131], v[228:229], v[224:225]
	v_lshlrev_b32_e32 v228, 16, v77
	v_and_b32_e32 v229, 0xffff0000, v77
	v_pk_fma_f32 v[226:227], v[106:107], v[228:229], 0 op_sel_hi:[1,1,0]
	v_lshlrev_b32_e32 v228, 16, v85
	v_and_b32_e32 v229, 0xffff0000, v85
	v_pk_fma_f32 v[226:227], v[122:123], v[228:229], v[226:227]
	v_lshlrev_b32_e32 v228, 16, v93
	v_and_b32_e32 v229, 0xffff0000, v93
	v_pk_fma_f32 v[226:227], v[138:139], v[228:229], v[226:227]
	v_pk_mul_f32 v[224:225], v[224:225], v[226:227]
	v_cvt_pk_bf16_f32 v230, v224, v225
	ds_write_b16 v219, v230 offset:9568
	ds_write_b16_d16_hi v219, v230 offset:9712
	v_lshlrev_b32_e32 v228, 16, v74
	v_and_b32_e32 v229, 0xffff0000, v74
	v_pk_fma_f32 v[224:225], v[100:101], v[228:229], 0 op_sel_hi:[1,1,0]
	v_lshlrev_b32_e32 v228, 16, v82
	v_and_b32_e32 v229, 0xffff0000, v82
	v_pk_fma_f32 v[224:225], v[116:117], v[228:229], v[224:225]
	v_lshlrev_b32_e32 v228, 16, v90
	v_and_b32_e32 v229, 0xffff0000, v90
	v_pk_fma_f32 v[224:225], v[132:133], v[228:229], v[224:225]
	v_lshlrev_b32_e32 v228, 16, v78
	v_and_b32_e32 v229, 0xffff0000, v78
	v_pk_fma_f32 v[226:227], v[108:109], v[228:229], 0 op_sel_hi:[1,1,0]
	v_lshlrev_b32_e32 v228, 16, v86
	v_and_b32_e32 v229, 0xffff0000, v86
	v_pk_fma_f32 v[226:227], v[124:125], v[228:229], v[226:227]
	v_lshlrev_b32_e32 v228, 16, v94
	v_and_b32_e32 v229, 0xffff0000, v94
	v_pk_fma_f32 v[226:227], v[140:141], v[228:229], v[226:227]
	v_pk_mul_f32 v[224:225], v[224:225], v[226:227]
	v_cvt_pk_bf16_f32 v230, v224, v225
	ds_write_b16 v219, v230 offset:9856
	ds_write_b16_d16_hi v219, v230 offset:10000
	v_lshlrev_b32_e32 v228, 16, v75
	v_and_b32_e32 v229, 0xffff0000, v75
	v_pk_fma_f32 v[224:225], v[102:103], v[228:229], 0 op_sel_hi:[1,1,0]
	v_lshlrev_b32_e32 v228, 16, v83
	v_and_b32_e32 v229, 0xffff0000, v83
	v_pk_fma_f32 v[224:225], v[118:119], v[228:229], v[224:225]
	v_lshlrev_b32_e32 v228, 16, v91
	v_and_b32_e32 v229, 0xffff0000, v91
	v_pk_fma_f32 v[224:225], v[134:135], v[228:229], v[224:225]
	v_lshlrev_b32_e32 v228, 16, v79
	v_and_b32_e32 v229, 0xffff0000, v79
	v_pk_fma_f32 v[226:227], v[110:111], v[228:229], 0 op_sel_hi:[1,1,0]
	v_lshlrev_b32_e32 v228, 16, v87
	v_and_b32_e32 v229, 0xffff0000, v87
	v_pk_fma_f32 v[226:227], v[126:127], v[228:229], v[226:227]
	v_lshlrev_b32_e32 v228, 16, v95
	v_and_b32_e32 v229, 0xffff0000, v95
	v_pk_fma_f32 v[226:227], v[142:143], v[228:229], v[226:227]
	v_pk_mul_f32 v[224:225], v[224:225], v[226:227]
	v_cvt_pk_bf16_f32 v230, v224, v225
	ds_write_b16 v219, v230 offset:10144
	ds_write_b16_d16_hi v219, v230 offset:10288
	s_waitcnt lgkmcnt(0)
	s_barrier
	ds_read_b128 v[232:235], v220 offset:9216
	ds_read_b128 v[236:239], v220 offset:13824
	s_waitcnt lgkmcnt(1)
	global_store_dwordx4 v[198:199], v[232:235], off
	s_waitcnt lgkmcnt(0)
	global_store_dwordx4 v[210:211], v[236:239], off
	v_lshl_add_u64 v[198:199], v[198:199], 0, s[50:51]
	v_lshl_add_u64 v[210:211], v[210:211], 0, s[50:51]
	s_branch .LBB0_858
; DI int tidx() { return tid512() & 255; }
; DI void hyena_pre_tile(const Params& p, int item, char* smem) {
;   const int tid = tidx();
;   const int ct = item & 7, st = (item >> 3) & 63, b = item >> 9;
;   const bf16_t* HY = (const bf16_t*)(p.ws + OFF_HY) + (size_t)b * 4096 * 1536;
;   bf16_t* sT = (bf16_t*)smem;
;   __syncthreads();
; #pragma unroll
;   for (int i = 0; i < 2; ++i) {
;     int row = (tid >> 3) + 32 * i, ck = tid & 7, s = st * 64 + row, c = ct * 64 + ck * 8;
;     float x1[8], vv[8];
; #pragma unroll
;     for (int j = 0; j < 8; ++j) { x1[j] = 0.f; vv[j] = 0.f; }
; #pragma unroll
;     for (int d = -1; d <= 1; ++d) {
;       int ss = s + d;
;       if (ss >= 0 && ss < 4096) {
;         u32x4 a = ldg16(HY + (size_t)ss * 1536 + 512 + c), bb = ldg16(HY + (size_t)ss * 1536 + 1024 + c);
;         float wa[8], wb[8]; ld8f(p.c_short + (d + 1) * 1536 + 512 + c, wa); ld8f(p.c_short + (d + 1) * 1536 + 1024 + c, wb);
.Lpre_fallback:
	s_add_i32 s34, s33, 0xfffff800
	s_lshr_b32 s62, s34, 9
	s_and_b32 s61, s33, 7
	s_mul_i32 s30, s62, 0xc00000
	v_mov_b32_e32 v0, v196
	s_add_u32 s30, s14, s30
	s_addc_u32 s31, s15, 0
	s_lshl_b32 s34, s34, 3
	v_bfe_u32 v52, v0, 3, 5
	s_and_b32 s63, s34, 0xfc0
	v_lshlrev_b32_e32 v0, 3, v0
	v_and_b32_e32 v53, 56, v0
	v_or_b32_e32 v0, s63, v52
	v_lshl_or_b32 v2, s61, 6, v53
	v_add_u32_e32 v1, -1, v0
	v_cmp_gt_u32_e32 vcc, s69, v1
	v_mov_b32_e32 v10, 0
	v_lshlrev_b32_e32 v8, 1, v2
	v_lshlrev_b32_e32 v48, 2, v2
	v_mov_b32_e32 v11, 0
	v_mov_b32_e32 v16, 0
	v_mov_b32_e32 v17, 0
	v_mov_b32_e32 v20, 0
	v_mov_b32_e32 v21, 0
	v_mov_b32_e32 v24, 0
	v_mov_b32_e32 v25, 0
	v_mov_b32_e32 v12, 0
	v_mov_b32_e32 v13, 0
	v_mov_b32_e32 v14, 0
	v_mov_b32_e32 v15, 0
	v_mov_b32_e32 v18, 0
	v_mov_b32_e32 v19, 0
	v_mov_b32_e32 v22, 0
	v_mov_b32_e32 v23, 0
	s_barrier
	s_and_saveexec_b64 s[34:35], vcc
	s_cbranch_execz .LBB0_851
	v_mul_i32_i24_e32 v68, 0x600, v1
	v_lshl_add_u64 v[2:3], v[68:69], 1, s[30:31]
	v_mov_b32_e32 v9, v69
	v_lshl_add_u64 v[6:7], v[2:3], 0, v[8:9]
	v_readlane_b32 s44, v247, 34
	global_load_dwordx4 v[2:5], v[6:7], off offset:1024
	global_load_dwordx4 v[22:25], v[6:7], off offset:2048
	v_readlane_b32 s50, v247, 40
	v_readlane_b32 s51, v247, 41
	s_nop 4
	global_load_dwordx4 v[26:29], v48, s[50:51] offset:2064
	global_load_dwordx4 v[12:15], v48, s[50:51] offset:2048
	global_load_dwordx4 v[30:33], v48, s[2:3] offset:16
	global_load_dwordx4 v[16:19], v48, s[2:3]
	v_readlane_b32 s45, v247, 35
	v_readlane_b32 s46, v247, 36
	v_readlane_b32 s47, v247, 37
	v_readlane_b32 s48, v247, 38
	v_readlane_b32 s49, v247, 39
	v_readlane_b32 s52, v247, 42
	v_readlane_b32 s53, v247, 43
	v_readlane_b32 s54, v247, 44
	v_readlane_b32 s55, v247, 45
	v_readlane_b32 s56, v247, 46
	v_readlane_b32 s57, v247, 47
	v_readlane_b32 s58, v247, 48
	v_readlane_b32 s59, v247, 49
	s_waitcnt vmcnt(5)
	v_lshlrev_b32_e32 v6, 16, v2
	v_and_b32_e32 v7, 0xffff0000, v2
	v_lshlrev_b32_e32 v2, 16, v3
	v_and_b32_e32 v3, 0xffff0000, v3
	s_waitcnt vmcnt(2)
	v_pk_fma_f32 v[12:13], v[12:13], v[6:7], 0 op_sel_hi:[1,1,0]
	v_lshlrev_b32_e32 v6, 16, v22
	v_and_b32_e32 v7, 0xffff0000, v22
	v_pk_fma_f32 v[14:15], v[14:15], v[2:3], 0 op_sel_hi:[1,1,0]
	v_lshlrev_b32_e32 v2, 16, v23
	v_and_b32_e32 v3, 0xffff0000, v23
	s_waitcnt vmcnt(0)
	v_pk_fma_f32 v[10:11], v[16:17], v[6:7], 0 op_sel_hi:[1,1,0]
	v_pk_fma_f32 v[16:17], v[18:19], v[2:3], 0 op_sel_hi:[1,1,0]
	v_lshlrev_b32_e32 v2, 16, v4
	v_and_b32_e32 v3, 0xffff0000, v4
	v_pk_fma_f32 v[18:19], v[26:27], v[2:3], 0 op_sel_hi:[1,1,0]
	v_lshlrev_b32_e32 v2, 16, v24
	v_and_b32_e32 v3, 0xffff0000, v24
	v_pk_fma_f32 v[20:21], v[30:31], v[2:3], 0 op_sel_hi:[1,1,0]
	v_lshlrev_b32_e32 v2, 16, v5
	v_and_b32_e32 v3, 0xffff0000, v5
	v_pk_fma_f32 v[22:23], v[28:29], v[2:3], 0 op_sel_hi:[1,1,0]
	v_lshlrev_b32_e32 v2, 16, v25
	v_and_b32_e32 v3, 0xffff0000, v25
	v_pk_fma_f32 v[24:25], v[32:33], v[2:3], 0 op_sel_hi:[1,1,0]
